# pass3 items taken from a device-wide atomic counter after the first static item (dynamic balancing against attention-time spread)
# speedup vs baseline: 1.0127x; 1.0057x over previous
; __device__ __forceinline__ float bf2f(unsigned v) { return __uint_as_float(v << 16); }
; template <int TYPE>
; __device__ __forceinline__ void pass3_item(const KArgs& a, int l, int item, LAS unsigned char* lds) {
;     ...
;     const float gain = ((const float*)a.in[TYPE ? 7 : 5])[l * 128 + wid * 16 + fr];
;     bf16_t* mix = (bf16_t*)(wsb + WS_XN);
;     float gtv[4][4];
; #pragma unroll
;     for (int it = 0; it < 4; ++it)
; #pragma unroll
;         for (int r = 0; r < 4; ++r) gtv[it][r] = bf2f(u[(tok0 + it * 16 + fq * 4 + r) * DINP + (TYPE ? C_HG : C_GG) + h * 128 + wid * 16 + fr]);
.LBB0_492:
	s_or_b64 exec, exec, s[6:7]
	v_readlane_b32 s6, v255, 29
	v_readlane_b32 s8, v253, 48
	v_readlane_b32 s22, v253, 62
	v_add_u32_e32 v16, s6, v64
	v_or_b32_e32 v16, v16, v89
	v_ashrrev_i32_e32 v17, 31, v16
	v_readlane_b32 s23, v253, 63
	v_readlane_b32 s9, v253, 49
	v_or_b32_e32 v42, s60, v83
	v_lshl_add_u64 v[16:17], v[16:17], 2, s[22:23]
	v_mov_b64_e32 v[50:51], s[62:63]
	s_movk_i32 s2, 0x2a00
	s_waitcnt lgkmcnt(0)
	s_barrier
	global_load_dword v52, v[16:17], off
	s_mul_i32 s6, s61, 0x2a00
	v_mad_u64_u32 v[16:17], s[8:9], v42, s2, v[50:51]
	v_ashrrev_i32_e32 v65, 31, v64
	v_add_u32_e32 v17, s6, v17
	s_lshl_b32 s72, s5, 1
	v_lshl_add_u64 v[16:17], v[16:17], 0, s[72:73]
	v_lshlrev_b64 v[24:25], 1, v[64:65]
	v_lshl_add_u64 v[16:17], v[16:17], 0, v[24:25]
	v_lshlrev_b32_e32 v112, 1, v89
	v_lshl_add_u64 v[16:17], v[16:17], 0, v[112:113]
	s_movk_i32 s77, 0x1000
	v_add_co_u32_e32 v16, vcc, s77, v16
	v_or_b32_e32 v44, 1, v42
	s_nop 0
	v_addc_co_u32_e32 v17, vcc, 0, v17, vcc
	global_load_ushort v142, v[16:17], off offset:3136
	v_or_b32_e32 v46, 2, v42
	v_or_b32_e32 v48, 3, v42
	v_or_b32_e32 v66, 16, v83
	v_or_b32_e32 v40, s60, v66
	v_or_b32_e32 v38, 17, v42
	v_or_b32_e32 v34, 18, v42
	v_or_b32_e32 v28, 19, v42
	v_or_b32_e32 v59, 32, v83
	v_or_b32_e32 v26, s60, v59
	v_or_b32_e32 v30, 33, v42
	v_or_b32_e32 v32, 34, v42
	v_or_b32_e32 v36, 35, v42
	v_or_b32_e32 v56, 48, v83
	v_or_b32_e32 v22, s60, v56
	v_or_b32_e32 v20, 49, v42
	v_or_b32_e32 v18, 50, v42
	v_mov_b32_e32 v43, s61
	v_mov_b32_e32 v45, s61
	v_mov_b32_e32 v47, s61
	v_mov_b32_e32 v49, s61
	v_mov_b32_e32 v41, s61
	v_mov_b32_e32 v39, s61
	v_mov_b32_e32 v35, s61
	v_mov_b32_e32 v29, s61
	v_mov_b32_e32 v27, s61
	v_mov_b32_e32 v31, s61
	v_mov_b32_e32 v33, s61
	v_mov_b32_e32 v37, s61
	v_mov_b32_e32 v23, s61
	v_mov_b32_e32 v21, s61
	v_mov_b32_e32 v19, s61
	v_readlane_b32 s68, v255, 16
	v_readlane_b32 s70, v255, 18
	v_readlane_b32 s69, v255, 17
	s_movk_i32 s66, 0x80
	s_movk_i32 s67, 0x100
	s_movk_i32 s3, 0x90
	v_readlane_b32 s10, v253, 50
	v_readlane_b32 s11, v253, 51
	v_readlane_b32 s12, v253, 52
	v_readlane_b32 s13, v253, 53
	v_readlane_b32 s14, v253, 54
	v_readlane_b32 s15, v253, 55
	v_readlane_b32 s16, v253, 56
	v_readlane_b32 s17, v253, 57
	v_readlane_b32 s18, v253, 58
	v_readlane_b32 s19, v253, 59
	v_readlane_b32 s20, v253, 60
	v_readlane_b32 s21, v253, 61
	v_readlane_b32 s71, v255, 19


; __device__ __forceinline__ float bf2f(unsigned v) { return __uint_as_float(v << 16); }
; template <int TYPE>
; __device__ __forceinline__ void pass3_item(const KArgs& a, int l, int item, LAS unsigned char* lds) {
;     ...
;         for (int r = 0; r < 4; ++r) gtv[it][r] = bf2f(u[(tok0 + it * 16 + fq * 4 + r) * DINP + (TYPE ? C_HG : C_GG) + h * 128 + wid * 16 + fr]);
	v_mad_u64_u32 v[16:17], s[8:9], v44, s2, v[50:51]
	v_add_u32_e32 v17, s6, v17
	v_lshl_add_u64 v[16:17], v[16:17], 0, s[72:73]
	v_lshl_add_u64 v[16:17], v[16:17], 0, v[24:25]
	v_lshl_add_u64 v[16:17], v[16:17], 0, v[112:113]
	v_add_co_u32_e32 v16, vcc, s77, v16
	s_nop 1
	v_addc_co_u32_e32 v17, vcc, 0, v17, vcc
	global_load_ushort v143, v[16:17], off offset:3136


; __device__ __forceinline__ float bf2f(unsigned v) { return __uint_as_float(v << 16); }
; template <int TYPE>
; __device__ __forceinline__ void pass3_item(const KArgs& a, int l, int item, LAS unsigned char* lds) {
;     ...
;         for (int r = 0; r < 4; ++r) gtv[it][r] = bf2f(u[(tok0 + it * 16 + fq * 4 + r) * DINP + (TYPE ? C_HG : C_GG) + h * 128 + wid * 16 + fr]);
	v_mad_u64_u32 v[16:17], s[8:9], v46, s2, v[50:51]
	v_add_u32_e32 v17, s6, v17
	v_lshl_add_u64 v[16:17], v[16:17], 0, s[72:73]
	v_lshl_add_u64 v[16:17], v[16:17], 0, v[24:25]
	v_lshl_add_u64 v[16:17], v[16:17], 0, v[112:113]
	v_add_co_u32_e32 v16, vcc, s77, v16
	s_nop 1
	v_addc_co_u32_e32 v17, vcc, 0, v17, vcc
	global_load_ushort v144, v[16:17], off offset:3136


; __device__ __forceinline__ float bf2f(unsigned v) { return __uint_as_float(v << 16); }
; template <int TYPE>
; __device__ __forceinline__ void pass3_item(const KArgs& a, int l, int item, LAS unsigned char* lds) {
;     ...
;         for (int r = 0; r < 4; ++r) gtv[it][r] = bf2f(u[(tok0 + it * 16 + fq * 4 + r) * DINP + (TYPE ? C_HG : C_GG) + h * 128 + wid * 16 + fr]);
	v_mad_u64_u32 v[16:17], s[8:9], v48, s2, v[50:51]
	v_add_u32_e32 v17, s6, v17
	v_lshl_add_u64 v[16:17], v[16:17], 0, s[72:73]
	v_lshl_add_u64 v[16:17], v[16:17], 0, v[24:25]
	v_lshl_add_u64 v[16:17], v[16:17], 0, v[112:113]
	v_add_co_u32_e32 v16, vcc, s77, v16
	s_nop 1
	v_addc_co_u32_e32 v17, vcc, 0, v17, vcc
	global_load_ushort v145, v[16:17], off offset:3136


; __device__ __forceinline__ float bf2f(unsigned v) { return __uint_as_float(v << 16); }
; template <int TYPE>
; __device__ __forceinline__ void pass3_item(const KArgs& a, int l, int item, LAS unsigned char* lds) {
;     ...
;         for (int r = 0; r < 4; ++r) gtv[it][r] = bf2f(u[(tok0 + it * 16 + fq * 4 + r) * DINP + (TYPE ? C_HG : C_GG) + h * 128 + wid * 16 + fr]);
	v_mad_u64_u32 v[16:17], s[8:9], v40, s2, v[50:51]
	v_add_u32_e32 v17, s6, v17
	v_lshl_add_u64 v[16:17], v[16:17], 0, s[72:73]
	v_lshl_add_u64 v[16:17], v[16:17], 0, v[24:25]
	v_lshl_add_u64 v[16:17], v[16:17], 0, v[112:113]
	v_add_co_u32_e32 v16, vcc, s77, v16
	v_lshlrev_b64 v[40:41], 12, v[40:41]
	s_nop 0
	v_addc_co_u32_e32 v17, vcc, 0, v17, vcc
	global_load_ushort v146, v[16:17], off offset:3136


; __device__ __forceinline__ float bf2f(unsigned v) { return __uint_as_float(v << 16); }
; template <int TYPE>
; __device__ __forceinline__ void pass3_item(const KArgs& a, int l, int item, LAS unsigned char* lds) {
;     ...
;         for (int r = 0; r < 4; ++r) gtv[it][r] = bf2f(u[(tok0 + it * 16 + fq * 4 + r) * DINP + (TYPE ? C_HG : C_GG) + h * 128 + wid * 16 + fr]);
	v_mad_u64_u32 v[16:17], s[8:9], v38, s2, v[50:51]
	v_add_u32_e32 v17, s6, v17
	v_lshl_add_u64 v[16:17], v[16:17], 0, s[72:73]
	v_lshl_add_u64 v[16:17], v[16:17], 0, v[24:25]
	v_lshl_add_u64 v[16:17], v[16:17], 0, v[112:113]
	v_add_co_u32_e32 v16, vcc, s77, v16
	s_nop 1
	v_addc_co_u32_e32 v17, vcc, 0, v17, vcc
	global_load_ushort v147, v[16:17], off offset:3136


; __device__ __forceinline__ float bf2f(unsigned v) { return __uint_as_float(v << 16); }
; template <int TYPE>
; __device__ __forceinline__ void pass3_item(const KArgs& a, int l, int item, LAS unsigned char* lds) {
;     ...
;         for (int r = 0; r < 4; ++r) gtv[it][r] = bf2f(u[(tok0 + it * 16 + fq * 4 + r) * DINP + (TYPE ? C_HG : C_GG) + h * 128 + wid * 16 + fr]);
	v_mad_u64_u32 v[16:17], s[8:9], v34, s2, v[50:51]
	v_add_u32_e32 v17, s6, v17
	v_lshl_add_u64 v[16:17], v[16:17], 0, s[72:73]
	v_lshl_add_u64 v[16:17], v[16:17], 0, v[24:25]
	v_lshl_add_u64 v[16:17], v[16:17], 0, v[112:113]
	v_add_co_u32_e32 v16, vcc, s77, v16
	s_nop 1
	v_addc_co_u32_e32 v17, vcc, 0, v17, vcc
	global_load_ushort v148, v[16:17], off offset:3136


; __device__ __forceinline__ float bf2f(unsigned v) { return __uint_as_float(v << 16); }
; template <int TYPE>
; __device__ __forceinline__ void pass3_item(const KArgs& a, int l, int item, LAS unsigned char* lds) {
;     ...
;         for (int r = 0; r < 4; ++r) gtv[it][r] = bf2f(u[(tok0 + it * 16 + fq * 4 + r) * DINP + (TYPE ? C_HG : C_GG) + h * 128 + wid * 16 + fr]);
	v_mad_u64_u32 v[16:17], s[8:9], v28, s2, v[50:51]
	v_add_u32_e32 v17, s6, v17
	v_lshl_add_u64 v[16:17], v[16:17], 0, s[72:73]
	v_lshl_add_u64 v[16:17], v[16:17], 0, v[24:25]
	v_lshl_add_u64 v[16:17], v[16:17], 0, v[112:113]
	v_add_co_u32_e32 v16, vcc, s77, v16
	s_nop 1
	v_addc_co_u32_e32 v17, vcc, 0, v17, vcc
	global_load_ushort v149, v[16:17], off offset:3136


; __device__ __forceinline__ float bf2f(unsigned v) { return __uint_as_float(v << 16); }
; template <int TYPE>
; __device__ __forceinline__ void pass3_item(const KArgs& a, int l, int item, LAS unsigned char* lds) {
;     ...
;         for (int r = 0; r < 4; ++r) gtv[it][r] = bf2f(u[(tok0 + it * 16 + fq * 4 + r) * DINP + (TYPE ? C_HG : C_GG) + h * 128 + wid * 16 + fr]);
	v_mad_u64_u32 v[16:17], s[8:9], v26, s2, v[50:51]
	v_add_u32_e32 v17, s6, v17
	v_lshl_add_u64 v[16:17], v[16:17], 0, s[72:73]
	v_lshl_add_u64 v[16:17], v[16:17], 0, v[24:25]
	v_lshl_add_u64 v[16:17], v[16:17], 0, v[112:113]
	v_add_co_u32_e32 v16, vcc, s77, v16
	s_nop 1
	v_addc_co_u32_e32 v17, vcc, 0, v17, vcc
	global_load_ushort v150, v[16:17], off offset:3136


; __device__ __forceinline__ float bf2f(unsigned v) { return __uint_as_float(v << 16); }
; template <int TYPE>
; __device__ __forceinline__ void pass3_item(const KArgs& a, int l, int item, LAS unsigned char* lds) {
;     ...
;         for (int r = 0; r < 4; ++r) gtv[it][r] = bf2f(u[(tok0 + it * 16 + fq * 4 + r) * DINP + (TYPE ? C_HG : C_GG) + h * 128 + wid * 16 + fr]);
	v_mad_u64_u32 v[16:17], s[8:9], v30, s2, v[50:51]
	v_add_u32_e32 v17, s6, v17
	v_lshl_add_u64 v[16:17], v[16:17], 0, s[72:73]
	v_lshl_add_u64 v[16:17], v[16:17], 0, v[24:25]
	v_lshl_add_u64 v[16:17], v[16:17], 0, v[112:113]
	v_add_co_u32_e32 v16, vcc, s77, v16
	s_nop 1
	v_addc_co_u32_e32 v17, vcc, 0, v17, vcc
	global_load_ushort v151, v[16:17], off offset:3136


; __device__ __forceinline__ float bf2f(unsigned v) { return __uint_as_float(v << 16); }
; template <int TYPE>
; __device__ __forceinline__ void pass3_item(const KArgs& a, int l, int item, LAS unsigned char* lds) {
;     ...
;         for (int r = 0; r < 4; ++r) gtv[it][r] = bf2f(u[(tok0 + it * 16 + fq * 4 + r) * DINP + (TYPE ? C_HG : C_GG) + h * 128 + wid * 16 + fr]);
	v_mad_u64_u32 v[16:17], s[8:9], v32, s2, v[50:51]
	v_add_u32_e32 v17, s6, v17
	v_lshl_add_u64 v[16:17], v[16:17], 0, s[72:73]
	v_lshl_add_u64 v[16:17], v[16:17], 0, v[24:25]
	v_lshl_add_u64 v[16:17], v[16:17], 0, v[112:113]
	v_add_co_u32_e32 v16, vcc, s77, v16
	s_nop 1
	v_addc_co_u32_e32 v17, vcc, 0, v17, vcc
	global_load_ushort v152, v[16:17], off offset:3136


; __device__ __forceinline__ float bf2f(unsigned v) { return __uint_as_float(v << 16); }
; template <int TYPE>
; __device__ __forceinline__ void pass3_item(const KArgs& a, int l, int item, LAS unsigned char* lds) {
;     ...
;         for (int r = 0; r < 4; ++r) gtv[it][r] = bf2f(u[(tok0 + it * 16 + fq * 4 + r) * DINP + (TYPE ? C_HG : C_GG) + h * 128 + wid * 16 + fr]);
	v_mad_u64_u32 v[16:17], s[8:9], v36, s2, v[50:51]
	v_add_u32_e32 v17, s6, v17
	v_lshl_add_u64 v[16:17], v[16:17], 0, s[72:73]
	v_lshl_add_u64 v[16:17], v[16:17], 0, v[24:25]
	v_lshl_add_u64 v[16:17], v[16:17], 0, v[112:113]
	v_add_co_u32_e32 v16, vcc, s77, v16
	s_nop 1
	v_addc_co_u32_e32 v17, vcc, 0, v17, vcc
	global_load_ushort v153, v[16:17], off offset:3136


; __device__ __forceinline__ float bf2f(unsigned v) { return __uint_as_float(v << 16); }
; template <int TYPE>
; __device__ __forceinline__ void pass3_item(const KArgs& a, int l, int item, LAS unsigned char* lds) {
;     ...
;         for (int r = 0; r < 4; ++r) gtv[it][r] = bf2f(u[(tok0 + it * 16 + fq * 4 + r) * DINP + (TYPE ? C_HG : C_GG) + h * 128 + wid * 16 + fr]);
	v_mad_u64_u32 v[16:17], s[8:9], v22, s2, v[50:51]
	v_add_u32_e32 v17, s6, v17
	v_lshl_add_u64 v[16:17], v[16:17], 0, s[72:73]
	v_lshl_add_u64 v[16:17], v[16:17], 0, v[24:25]
	v_lshl_add_u64 v[16:17], v[16:17], 0, v[112:113]
	v_add_co_u32_e32 v16, vcc, s77, v16
	s_nop 1
	v_addc_co_u32_e32 v17, vcc, 0, v17, vcc
	global_load_ushort v154, v[16:17], off offset:3136


; __device__ __forceinline__ float bf2f(unsigned v) { return __uint_as_float(v << 16); }
; template <int TYPE>
; __device__ __forceinline__ void pass3_item(const KArgs& a, int l, int item, LAS unsigned char* lds) {
;     ...
;         for (int r = 0; r < 4; ++r) gtv[it][r] = bf2f(u[(tok0 + it * 16 + fq * 4 + r) * DINP + (TYPE ? C_HG : C_GG) + h * 128 + wid * 16 + fr]);
	v_mad_u64_u32 v[16:17], s[8:9], v20, s2, v[50:51]
	v_add_u32_e32 v17, s6, v17
	v_lshl_add_u64 v[16:17], v[16:17], 0, s[72:73]
	v_lshl_add_u64 v[16:17], v[16:17], 0, v[24:25]
	v_lshl_add_u64 v[16:17], v[16:17], 0, v[112:113]
	v_add_co_u32_e32 v16, vcc, s77, v16
	s_nop 1
	v_addc_co_u32_e32 v17, vcc, 0, v17, vcc
	global_load_ushort v155, v[16:17], off offset:3136


; __device__ __forceinline__ float bf2f(unsigned v) { return __uint_as_float(v << 16); }
; template <int TYPE>
; __device__ __forceinline__ void pass3_item(const KArgs& a, int l, int item, LAS unsigned char* lds) {
;     ...
;         for (int r = 0; r < 4; ++r) gtv[it][r] = bf2f(u[(tok0 + it * 16 + fq * 4 + r) * DINP + (TYPE ? C_HG : C_GG) + h * 128 + wid * 16 + fr]);
	v_mad_u64_u32 v[16:17], s[8:9], v18, s2, v[50:51]
	v_add_u32_e32 v17, s6, v17
	v_lshl_add_u64 v[16:17], v[16:17], 0, s[72:73]
	v_lshl_add_u64 v[16:17], v[16:17], 0, v[24:25]
	v_lshl_add_u64 v[16:17], v[16:17], 0, v[112:113]
	v_add_co_u32_e32 v16, vcc, s77, v16
	s_nop 1
	v_addc_co_u32_e32 v17, vcc, 0, v17, vcc
	global_load_ushort v156, v[16:17], off offset:3136
	v_mov_b32_e32 v17, s61

; __device__ __forceinline__ unsigned f2bf(float f) { unsigned u = __float_as_uint(f); return (u + 0x7fffu + ((u >> 16) & 1u)) >> 16; }
; __device__ __forceinline__ float silu_(float z) { return z * sigmoid_(z); }
; template <int TYPE>
; __device__ __forceinline__ void pass3_item(const KArgs& a, int l, int item, LAS unsigned char* lds) {
;     ...
; #pragma unroll
;     for (int it = 0; it < 4; ++it)
; #pragma unroll
;         for (int r = 0; r < 4; ++r) { const int i = it * 16 + fq * 4 + r;
;             const float rstd = RSTD[i];
;             const float gt = gtv[it][r];
;             const float yv = o[it][r] * rstd * gain * silu_(gt);
;             mix[(tok0 + i) * DM + (TYPE ? 512 : 0) + h * 128 + wid * 16 + fr] = (bf16_t)f2bf(yv); }
	s_waitcnt vmcnt(0) lgkmcnt(0)
	v_lshlrev_b32_e32 v67, 16, v142
	v_lshlrev_b32_e32 v68, 16, v143
	v_lshlrev_b32_e32 v69, 16, v144
	v_lshlrev_b32_e32 v70, 16, v145
	v_lshlrev_b32_e32 v65, 16, v146
	v_lshlrev_b32_e32 v64, 16, v147
	v_lshlrev_b32_e32 v62, 16, v148
	v_lshlrev_b32_e32 v60, 16, v149
	v_lshlrev_b32_e32 v57, 16, v150
	v_lshlrev_b32_e32 v58, 16, v151
	v_lshlrev_b32_e32 v61, 16, v152
	v_lshlrev_b32_e32 v63, 16, v153
	v_lshlrev_b32_e32 v55, 16, v154
	v_lshlrev_b32_e32 v54, 16, v155
	v_lshlrev_b32_e32 v53, 16, v156
	v_or_b32_e32 v16, 51, v42
	v_mad_u64_u32 v[50:51], s[8:9], v16, s2, v[50:51]
	v_add_u32_e32 v51, s6, v51
	v_lshl_add_u64 v[50:51], v[50:51], 0, s[72:73]
	v_lshl_add_u64 v[50:51], v[50:51], 0, v[24:25]
	v_lshl_add_u64 v[50:51], v[50:51], 0, v[112:113]
	v_add_co_u32_e32 v50, vcc, s77, v50
	s_add_u32 s6, s58, s72
	s_nop 0
	v_addc_co_u32_e32 v51, vcc, 0, v51, vcc
	global_load_ushort v50, v[50:51], off offset:3136
	v_lshl_add_u32 v51, v83, 2, s74
	ds_read_b128 v[72:75], v51
	v_mul_f32_e32 v51, 0xbfb8aa3b, v67
	v_exp_f32_e32 v51, v51
	s_addc_u32 s7, s59, 0
	v_lshl_add_u64 v[24:25], s[6:7], 0, v[24:25]
	s_waitcnt lgkmcnt(0)
	v_mul_f32_e32 v12, v12, v72
	v_add_f32_e32 v51, 1.0, v51
	v_rcp_f32_e32 v51, v51
	v_mul_f32_e32 v12, v52, v12
	v_lshl_add_u64 v[24:25], v[24:25], 0, v[112:113]
	s_mov_b64 s[6:7], 0x6300400
	v_mul_f32_e32 v51, v51, v67
	v_mul_f32_e32 v12, v51, v12
	v_lshl_add_u64 v[24:25], v[24:25], 0, s[6:7]
	v_bfe_u32 v51, v12, 16, 1
	v_lshlrev_b64 v[42:43], 12, v[42:43]
	v_add3_u32 v12, v12, v51, s1
	v_lshl_add_u64 v[42:43], v[24:25], 0, v[42:43]
	global_store_short_d16_hi v[42:43], v12, off
	v_mul_f32_e32 v12, v13, v73
	v_mul_f32_e32 v13, 0xbfb8aa3b, v68
	v_exp_f32_e32 v13, v13
	v_mul_f32_e32 v12, v52, v12
	v_lshl_add_u64 v[40:41], v[24:25], 0, v[40:41]
	s_add_i32 s4, s4, s70
	v_add_f32_e32 v13, 1.0, v13
	v_rcp_f32_e32 v13, v13
	s_cmpk_gt_i32 s4, 0x7ff
	v_mul_f32_e32 v13, v13, v68
	v_mul_f32_e32 v12, v13, v12
	v_bfe_u32 v13, v12, 16, 1
	v_add3_u32 v42, v12, v13, s1
	v_lshlrev_b64 v[12:13], 12, v[44:45]
	v_lshl_add_u64 v[12:13], v[24:25], 0, v[12:13]
	global_store_short_d16_hi v[12:13], v42, off
	v_mul_f32_e32 v13, 0xbfb8aa3b, v69
	v_exp_f32_e32 v13, v13
	v_mul_f32_e32 v12, v14, v74
	v_mul_f32_e32 v12, v52, v12
	v_add_f32_e32 v13, 1.0, v13
	v_rcp_f32_e32 v13, v13
	s_waitcnt vmcnt(0)
	v_lshlrev_b32_e32 v50, 16, v50
	v_mul_f32_e32 v13, v13, v69
	v_mul_f32_e32 v12, v13, v12
	v_bfe_u32 v13, v12, 16, 1
	v_add3_u32 v14, v12, v13, s1
	v_lshlrev_b64 v[12:13], 12, v[46:47]
	v_lshl_add_u64 v[12:13], v[24:25], 0, v[12:13]
	global_store_short_d16_hi v[12:13], v14, off
	v_mul_f32_e32 v13, 0xbfb8aa3b, v70
	v_exp_f32_e32 v13, v13
	v_mul_f32_e32 v12, v15, v75
	v_mul_f32_e32 v12, v52, v12
	v_add_f32_e32 v13, 1.0, v13
	v_rcp_f32_e32 v13, v13
	s_nop 0
	v_mul_f32_e32 v13, v13, v70
	v_mul_f32_e32 v12, v13, v12
	v_bfe_u32 v13, v12, 16, 1
	v_add3_u32 v14, v12, v13, s1
	v_lshlrev_b64 v[12:13], 12, v[48:49]
	v_lshl_add_u64 v[12:13], v[24:25], 0, v[12:13]
	global_store_short_d16_hi v[12:13], v14, off
	v_lshl_add_u32 v12, v66, 2, s74
	ds_read_b128 v[12:15], v12
	s_waitcnt lgkmcnt(0)
	v_mul_f32_e32 v8, v8, v12
	v_mul_f32_e32 v12, 0xbfb8aa3b, v65
	v_exp_f32_e32 v12, v12
	v_mul_f32_e32 v8, v52, v8
	v_add_f32_e32 v12, 1.0, v12
	v_rcp_f32_e32 v12, v12
	s_nop 0
	v_mul_f32_e32 v12, v12, v65
	v_mul_f32_e32 v8, v12, v8
	v_bfe_u32 v12, v8, 16, 1
	v_add3_u32 v8, v8, v12, s1
	global_store_short_d16_hi v[40:41], v8, off
	v_mul_f32_e32 v8, v9, v13
	v_mul_f32_e32 v9, 0xbfb8aa3b, v64
	v_exp_f32_e32 v9, v9
	v_mul_f32_e32 v8, v52, v8
	v_add_f32_e32 v9, 1.0, v9
	v_rcp_f32_e32 v9, v9
	s_nop 0
	v_mul_f32_e32 v9, v9, v64
	v_mul_f32_e32 v8, v9, v8
	v_bfe_u32 v9, v8, 16, 1
	v_add3_u32 v12, v8, v9, s1
	v_lshlrev_b64 v[8:9], 12, v[38:39]
	v_lshl_add_u64 v[8:9], v[24:25], 0, v[8:9]
	global_store_short_d16_hi v[8:9], v12, off
	v_mul_f32_e32 v9, 0xbfb8aa3b, v62
	v_exp_f32_e32 v9, v9
	v_mul_f32_e32 v8, v10, v14
	v_mul_f32_e32 v8, v52, v8
	v_lshlrev_b64 v[12:13], 12, v[26:27]
	v_add_f32_e32 v9, 1.0, v9
	v_rcp_f32_e32 v9, v9
	v_lshl_add_u64 v[12:13], v[24:25], 0, v[12:13]
	v_mul_f32_e32 v9, v9, v62
	v_mul_f32_e32 v8, v9, v8
	v_bfe_u32 v9, v8, 16, 1
	v_add3_u32 v10, v8, v9, s1
	v_lshlrev_b64 v[8:9], 12, v[34:35]
	v_lshl_add_u64 v[8:9], v[24:25], 0, v[8:9]
	global_store_short_d16_hi v[8:9], v10, off
	v_mul_f32_e32 v9, 0xbfb8aa3b, v60
	v_exp_f32_e32 v9, v9
	v_mul_f32_e32 v8, v11, v15
	v_mul_f32_e32 v8, v52, v8
	v_add_f32_e32 v9, 1.0, v9
	v_rcp_f32_e32 v9, v9
	s_nop 0
	v_mul_f32_e32 v9, v9, v60
	v_mul_f32_e32 v8, v9, v8
	v_bfe_u32 v9, v8, 16, 1
	v_add3_u32 v10, v8, v9, s1
	v_lshlrev_b64 v[8:9], 12, v[28:29]
	v_lshl_add_u64 v[8:9], v[24:25], 0, v[8:9]
	global_store_short_d16_hi v[8:9], v10, off
	v_lshl_add_u32 v8, v59, 2, s74
	ds_read_b128 v[8:11], v8
	s_waitcnt lgkmcnt(0)
; #define LAS __attribute__((address_space(3)))
; __device__ __forceinline__ unsigned f2bf(float f) { unsigned u = __float_as_uint(f); return (u + 0x7fffu + ((u >> 16) & 1u)) >> 16; }
; __device__ __forceinline__ float silu_(float z) { return z * sigmoid_(z); }
; template <int TYPE>
; __device__ __forceinline__ void pass3_item(const KArgs& a, int l, int item, LAS unsigned char* lds) {
;     ...
;     const int c = item & (NCH - 1), h = (item >> 8) & 3, b = item >> 10;
;     const size_t tok0 = (size_t)b * T + (size_t)c * 64;
;     const bf16_t* u = (const bf16_t*)(wsb + WS_U);
;     const int wid = tid >> 6, lane = tid & 63, fr = lane & 15, fq = lane >> 4;
;     LAS float* G = (LAS float*)(lds + SC_G); LAS bf16_t* Kb = (LAS bf16_t*)(lds + SC_K); LAS bf16_t* QT = (LAS bf16_t*)(lds + SC_QT); LAS bf16_t* QG = (LAS bf16_t*)(lds + SC_QG);
;     LAS bf16_t* VT = (LAS bf16_t*)(lds + SC_VT); LAS bf16_t* P = (LAS bf16_t*)(lds + SC_P); LAS float* RSQ = (LAS float*)(lds + SC_RSQ);
;     const VRaw vr = vT_issue(u + tok0 * DINP + (TYPE ? C_HI : C_GV) + h * 128, tid);
;     bf16x8 qraw[DK / 64];
; #pragma unroll
;     for (int e2 = 0; e2 < DK / 64; ++e2) { const int task = tid + 512 * e2, i = task / C::ND8, d8 = task % C::ND8;
;         qraw[e2] = *(const bf16x8*)(u + (tok0 + i) * DINP + (TYPE ? C_HQ + h * 128 : C_GQ + h * 64) + d8 * 8); }
;     const LgRaw raw0 = lg_issue<TYPE>(u, h, 0, tok0, tid), raw1 = lg_issue<TYPE>(u, h, 1, tok0, tid);
;     ...
; #pragma unroll
;     for (int it = 0; it < 4; ++it)
; #pragma unroll
;         for (int r = 0; r < 4; ++r) { const int i = it * 16 + fq * 4 + r;
;             const float rstd = RSTD[i];
;             const float gt = gtv[it][r];
;             const float yv = o[it][r] * rstd * gain * silu_(gt);
;             mix[(tok0 + i) * DM + (TYPE ? 512 : 0) + h * 128 + wid * 16 + fr] = (bf16_t)f2bf(yv); }
	v_mul_f32_e32 v4, v4, v8
	v_mul_f32_e32 v8, 0xbfb8aa3b, v57
	v_exp_f32_e32 v8, v8
	v_mul_f32_e32 v4, v52, v4
	v_add_f32_e32 v8, 1.0, v8
	v_rcp_f32_e32 v8, v8
	s_nop 0
	v_mul_f32_e32 v8, v8, v57
	v_mul_f32_e32 v4, v8, v4
	v_bfe_u32 v8, v4, 16, 1
	v_add3_u32 v4, v4, v8, s1
	global_store_short_d16_hi v[12:13], v4, off
	v_mul_f32_e32 v4, v5, v9
	v_mul_f32_e32 v5, 0xbfb8aa3b, v58
	v_exp_f32_e32 v5, v5
	v_mul_f32_e32 v4, v52, v4
	v_add_f32_e32 v5, 1.0, v5
	v_rcp_f32_e32 v5, v5
	s_nop 0
	v_mul_f32_e32 v5, v5, v58
	v_mul_f32_e32 v4, v5, v4
	v_bfe_u32 v5, v4, 16, 1
	v_add3_u32 v8, v4, v5, s1
	v_lshlrev_b64 v[4:5], 12, v[30:31]
	v_lshl_add_u64 v[4:5], v[24:25], 0, v[4:5]
	global_store_short_d16_hi v[4:5], v8, off
	v_mul_f32_e32 v5, 0xbfb8aa3b, v61
	v_exp_f32_e32 v5, v5
	v_mul_f32_e32 v4, v6, v10
	v_mul_f32_e32 v4, v52, v4
	v_lshlrev_b64 v[8:9], 12, v[22:23]
	v_add_f32_e32 v5, 1.0, v5
	v_rcp_f32_e32 v5, v5
	v_lshl_add_u64 v[8:9], v[24:25], 0, v[8:9]
	v_mul_f32_e32 v5, v5, v61
	v_mul_f32_e32 v4, v5, v4
	v_bfe_u32 v5, v4, 16, 1
	v_add3_u32 v6, v4, v5, s1
	v_lshlrev_b64 v[4:5], 12, v[32:33]
	v_lshl_add_u64 v[4:5], v[24:25], 0, v[4:5]
	global_store_short_d16_hi v[4:5], v6, off
	v_mul_f32_e32 v5, 0xbfb8aa3b, v63
	v_exp_f32_e32 v5, v5
	v_mul_f32_e32 v4, v7, v11
	v_mul_f32_e32 v4, v52, v4
	v_add_f32_e32 v5, 1.0, v5
	v_rcp_f32_e32 v5, v5
	s_nop 0
	v_mul_f32_e32 v5, v5, v63
	v_mul_f32_e32 v4, v5, v4
	v_bfe_u32 v5, v4, 16, 1
	v_add3_u32 v6, v4, v5, s1
	v_lshlrev_b64 v[4:5], 12, v[36:37]
	v_lshl_add_u64 v[4:5], v[24:25], 0, v[4:5]
	global_store_short_d16_hi v[4:5], v6, off
	v_lshl_add_u32 v4, v56, 2, s74
	ds_read_b128 v[4:7], v4
	s_waitcnt lgkmcnt(0)
	v_mul_f32_e32 v0, v0, v4
	v_mul_f32_e32 v4, 0xbfb8aa3b, v55
	v_exp_f32_e32 v4, v4
	v_mul_f32_e32 v0, v52, v0
	v_add_f32_e32 v4, 1.0, v4
	v_rcp_f32_e32 v4, v4
	s_nop 0
	v_mul_f32_e32 v4, v4, v55
	v_mul_f32_e32 v0, v4, v0
	v_bfe_u32 v4, v0, 16, 1
	v_add3_u32 v0, v0, v4, s1
	global_store_short_d16_hi v[8:9], v0, off
	v_mul_f32_e32 v0, v1, v5
	v_mul_f32_e32 v1, 0xbfb8aa3b, v54
	v_exp_f32_e32 v1, v1
	v_mul_f32_e32 v0, v52, v0
	v_add_f32_e32 v1, 1.0, v1
	v_rcp_f32_e32 v1, v1
	s_nop 0
	v_mul_f32_e32 v1, v1, v54
	v_mul_f32_e32 v0, v1, v0
	v_bfe_u32 v1, v0, 16, 1
	v_add3_u32 v4, v0, v1, s1
	v_lshlrev_b64 v[0:1], 12, v[20:21]
	v_lshl_add_u64 v[0:1], v[24:25], 0, v[0:1]
	global_store_short_d16_hi v[0:1], v4, off
	v_mul_f32_e32 v1, 0xbfb8aa3b, v53
	v_exp_f32_e32 v1, v1
	v_mul_f32_e32 v0, v2, v6
	v_mul_f32_e32 v0, v52, v0
	v_add_f32_e32 v1, 1.0, v1
	v_rcp_f32_e32 v1, v1
	s_nop 0
	v_mul_f32_e32 v1, v1, v53
	v_mul_f32_e32 v0, v1, v0
	v_bfe_u32 v1, v0, 16, 1
	v_add3_u32 v2, v0, v1, s1
	v_lshlrev_b64 v[0:1], 12, v[18:19]
	v_lshl_add_u64 v[0:1], v[24:25], 0, v[0:1]
	global_store_short_d16_hi v[0:1], v2, off
	v_mul_f32_e32 v1, 0xbfb8aa3b, v50
	v_exp_f32_e32 v1, v1
	v_mul_f32_e32 v0, v3, v7
	v_mul_f32_e32 v0, v52, v0
	v_add_f32_e32 v1, 1.0, v1
	v_rcp_f32_e32 v1, v1
	s_nop 0
	v_mul_f32_e32 v1, v1, v50
	v_mul_f32_e32 v0, v1, v0
	v_bfe_u32 v1, v0, 16, 1
	v_add3_u32 v2, v0, v1, s1
	v_lshlrev_b64 v[0:1], 12, v[16:17]
	v_lshl_add_u64 v[0:1], v[24:25], 0, v[0:1]
	global_store_short_d16_hi v[0:1], v2, off
	v_mov_b32_e32 v250, 0x1f000
	s_mov_b64 s[96:97], exec
	s_mov_b64 exec, s[88:89]
	s_cbranch_execz .Lat_p3h_nw
	ds_write_b32 v250, v249
.Lat_p3h_nw:
	s_mov_b64 exec, s[96:97]
	s_waitcnt lgkmcnt(0)
	s_barrier
	ds_read_b32 v249, v250
	s_waitcnt lgkmcnt(0)
	v_readfirstlane_b32 s4, v249
	s_addk_i32 s4, 0x100
	s_cmpk_gt_i32 s4, 0x7ff
	s_cbranch_scc1 .LBB0_508
.LBB0_493:
	v_cmp_eq_u32_e64 s[88:89], 0, v195
	s_mov_b64 s[96:97], exec
	v_readlane_b32 s98, v255, 11
	s_nop 1
	s_mov_b64 exec, s[88:89]
	s_cbranch_execz .Lat_p3h_na
	v_mov_b32_e32 v250, s98
	v_lshlrev_b32_e32 v250, 5, v250
	v_add_u32_e32 v250, 0x3e303800, v250
	v_mov_b32_e32 v251, 0
	v_lshl_add_u64 v[250:251], s[68:69], 0, v[250:251]
	v_mov_b32_e32 v249, 1
	global_atomic_add v249, v[250:251], v249, off sc0
.Lat_p3h_na:
	s_mov_b64 exec, s[96:97]
	s_ashr_i32 s6, s4, 10
	s_and_b32 s57, s4, 0xff
	s_ashr_i32 s7, s6, 31
	s_lshl_b64 s[60:61], s[6:7], 14
	s_lshl_b32 s5, s57, 6
	s_mov_b64 s[58:59], s[68:69]
	s_bfe_u32 s8, s4, 0x20008
	s_or_b32 s60, s60, s5
	s_add_u32 s62, s58, 0xe300000
	s_mul_i32 s5, s61, 0x2a00
	s_mul_hi_u32 s7, s60, 0x2a00
	s_addc_u32 s63, s59, 0
	s_add_i32 s7, s7, s5
	s_mul_i32 s5, s60, 0x2a00
	s_add_u32 s9, s62, s5
	s_addc_u32 s7, s63, s7
	s_lshl_b32 s5, s8, 7
	s_lshl_b32 s12, s8, 8
	s_add_u32 s9, s9, s12
	s_addc_u32 s7, s7, 0
	v_mov_b32_e32 v65, v195
	s_add_u32 s10, s9, 0x1840
	s_addc_u32 s11, s7, 0
	v_ashrrev_i32_e32 v0, 4, v65
	v_lshlrev_b32_e32 v40, 3, v65
	v_mov_b64_e32 v[2:3], s[10:11]
	v_and_b32_e32 v42, 0x78, v40
	v_add_u32_e32 v1, 32, v0
	v_ashrrev_i32_e32 v43, 31, v65
	v_mad_i64_i32 v[4:5], s[10:11], v0, s2, v[2:3]
	v_lshlrev_b32_e32 v112, 1, v42
	v_mad_i64_i32 v[2:3], s[10:11], v1, s2, v[2:3]
	v_lshrrev_b32_e32 v1, 28, v43
	v_lshl_add_u64 v[4:5], v[4:5], 0, v[112:113]
	v_add_u32_e32 v1, v65, v1
	global_load_dwordx4 v[6:9], v[4:5], off
	v_lshl_add_u64 v[4:5], v[2:3], 0, v[112:113]
	s_add_u32 s10, s62, s12
	v_ashrrev_i32_e32 v2, 4, v1
	s_addc_u32 s11, s63, 0
	v_and_b32_e32 v1, -16, v1
	v_ashrrev_i32_e32 v3, 31, v2
	v_sub_u32_e32 v44, v65, v1
	v_lshl_add_u64 v[14:15], s[60:61], 0, v[2:3]
	v_mov_b64_e32 v[16:17], s[10:11]
	global_load_dwordx4 v[10:13], v[4:5], off
	v_mad_u64_u32 v[4:5], s[10:11], v14, s2, v[16:17]
	v_lshlrev_b32_e32 v14, 3, v44
	v_mad_i32_i24 v5, v15, s2, v5
	v_ashrrev_i32_e32 v15, 31, v14
	v_lshl_add_u64 v[4:5], v[14:15], 1, v[4:5]
	global_load_dwordx4 v[32:35], v[4:5], off offset:3136
	v_add_u32_e32 v5, 0x200, v65
	v_ashrrev_i32_e32 v4, 31, v5
; __device__ __forceinline__ float silu_(float z) { return z * sigmoid_(z); }
; template <int TYPE>
; __device__ __forceinline__ void pass3_item(const KArgs& a, int l, int item, LAS unsigned char* lds) {
;     ...
;     const VRaw vr = vT_issue(u + tok0 * DINP + (TYPE ? C_HI : C_GV) + h * 128, tid);
;     bf16x8 qraw[DK / 64];
; #pragma unroll
;     for (int e2 = 0; e2 < DK / 64; ++e2) { const int task = tid + 512 * e2, i = task / C::ND8, d8 = task % C::ND8;
;         qraw[e2] = *(const bf16x8*)(u + (tok0 + i) * DINP + (TYPE ? C_HQ + h * 128 : C_GQ + h * 64) + d8 * 8); }
;     const LgRaw raw0 = lg_issue<TYPE>(u, h, 0, tok0, tid), raw1 = lg_issue<TYPE>(u, h, 1, tok0, tid);
;     __syncthreads();
;     vT_write(vr, lds, tid);
;     float qf[DK / 64][8];
; #pragma unroll
;     for (int e2 = 0; e2 < DK / 64; ++e2) { unpack8(qraw[e2], qf[e2]);
; #pragma unroll
;         for (int e = 0; e < 8; ++e) qf[e2][e] = TYPE ? silu_(qf[e2][e]) : qf[e2][e] * 0.125f; }
	v_lshrrev_b32_e32 v4, 28, v4
	v_add_u32_e32 v14, v5, v4
	v_ashrrev_i32_e32 v4, 4, v14
	v_and_b32_e32 v14, -16, v14
	v_sub_u32_e32 v45, v5, v14
	v_ashrrev_i32_e32 v5, 31, v4
	v_lshl_add_u64 v[14:15], s[60:61], 0, v[4:5]
	v_mad_u64_u32 v[16:17], s[10:11], v14, s2, v[16:17]
	v_lshlrev_b32_e32 v14, 3, v45
	v_mad_i32_i24 v17, v15, s2, v17
	v_ashrrev_i32_e32 v15, 31, v14
	v_lshl_add_u64 v[14:15], v[14:15], 1, v[16:17]
	global_load_dwordx4 v[36:39], v[14:15], off offset:3136
	v_ashrrev_i32_e32 v1, 31, v0
	v_lshl_add_u64 v[14:15], s[60:61], 0, v[0:1]
	v_mov_b64_e32 v[16:17], s[62:63]
	v_mad_u64_u32 v[24:25], s[10:11], v14, s2, v[16:17]
	v_or_b32_e32 v1, s5, v42
	v_mad_i32_i24 v25, v15, s2, v25
	v_lshlrev_b32_e32 v1, 1, v1
	s_mov_b64 s[10:11], 0x54000
	v_add_u32_e32 v14, 0x1040, v1
	v_mov_b32_e32 v15, v113
	v_lshl_add_u64 v[26:27], v[24:25], 0, s[10:11]
	v_lshl_add_u64 v[16:17], v[24:25], 0, v[14:15]
	v_lshl_add_u64 v[14:15], v[26:27], 0, v[14:15]
	global_load_dwordx4 v[16:19], v[16:17], off
	s_nop 0
	global_load_dwordx4 v[20:23], v[14:15], off
	v_add_u32_e32 v14, 0x1440, v1
	v_mov_b32_e32 v15, v113
	v_and_b32_e32 v1, 56, v40
	v_lshlrev_b32_e32 v5, 1, v0
	v_lshl_add_u64 v[24:25], v[24:25], 0, v[14:15]
	v_lshl_add_u64 v[14:15], v[26:27], 0, v[14:15]
	v_and_b32_e32 v5, 14, v5
	v_bitop3_b32 v1, v0, v1, -8 bitop3:0x6c
	global_load_dwordx4 v[24:27], v[24:25], off
	s_nop 0
	global_load_dwordx4 v[28:31], v[14:15], off
	v_add_u32_e32 v5, s95, v5
	v_lshlrev_b32_e32 v1, 1, v1
	v_mul_u32_u24_e32 v15, 0x90, v42
	v_and_b32_e32 v14, -8, v0
	v_add3_u32 v1, v5, v1, v15
	s_waitcnt lgkmcnt(0)
	s_barrier
	s_waitcnt vmcnt(0)
	ds_write_b16 v1, v6
	ds_write_b16_d16_hi v1, v6 offset:144
	ds_write_b16 v1, v7 offset:288
	ds_write_b16_d16_hi v1, v7 offset:432
	ds_write_b16 v1, v8 offset:576
	ds_write_b16_d16_hi v1, v8 offset:720
	ds_write_b16 v1, v9 offset:864
	ds_write_b16_d16_hi v1, v9 offset:1008
	v_add_u32_e32 v1, 32, v14
	v_bitop3_b32 v1, v1, v40, 56 bitop3:0x78
	v_lshlrev_b32_e32 v1, 1, v1
	v_add3_u32 v1, v5, v1, v15
	ds_write_b16 v1, v10
	ds_write_b16_d16_hi v1, v10 offset:144
	ds_write_b16 v1, v11 offset:288
	ds_write_b16_d16_hi v1, v11 offset:432
	ds_write_b16 v1, v12 offset:576
	ds_write_b16_d16_hi v1, v12 offset:720
	ds_write_b16 v1, v13 offset:864
	ds_write_b16_d16_hi v1, v13 offset:1008
	v_ashrrev_i32_e32 v3, 6, v65
	v_and_b32_e32 v89, 15, v65
	v_lshlrev_b32_e32 v64, 4, v3
	s_lshl_b32 s6, s6, 3
	s_lshl_b32 s7, s8, 1
	v_mov_b32_e32 v83, v113
	v_lshlrev_b32_e32 v6, 16, v32
	v_and_b32_e32 v7, 0xffff0000, v32
	v_mul_f32_e32 v1, 0xbfb8aa3b, v6
	v_exp_f32_e32 v1, v1
	v_mul_f32_e32 v5, 0xbfb8aa3b, v7
	v_exp_f32_e32 v5, v5
	v_lshlrev_b32_e32 v8, 16, v33
	v_add_f32_e32 v1, 1.0, v1
	v_and_b32_e32 v9, 0xffff0000, v33
	v_rcp_f32_e32 v14, v1
	v_add_f32_e32 v1, 1.0, v5
	v_mul_f32_e32 v5, 0xbfb8aa3b, v8
	v_exp_f32_e32 v5, v5
	v_mul_f32_e32 v15, 0xbfb8aa3b, v9
	v_exp_f32_e32 v33, v15
	v_lshlrev_b32_e32 v10, 16, v34
	v_and_b32_e32 v11, 0xffff0000, v34
	v_rcp_f32_e32 v15, v1
	v_add_f32_e32 v1, 1.0, v5
	v_mul_f32_e32 v5, 0xbfb8aa3b, v10
	v_rcp_f32_e32 v32, v1
	v_add_f32_e32 v1, 1.0, v33
	v_exp_f32_e32 v5, v5
	v_mul_f32_e32 v33, 0xbfb8aa3b, v11
	v_and_b32_e32 v13, 0xffff0000, v35
	v_lshlrev_b32_e32 v12, 16, v35
	v_exp_f32_e32 v35, v33
	v_rcp_f32_e32 v33, v1
	v_add_f32_e32 v1, 1.0, v5
	v_mul_f32_e32 v5, 0xbfb8aa3b, v12
	v_rcp_f32_e32 v34, v1
	v_add_f32_e32 v1, 1.0, v35
	v_exp_f32_e32 v5, v5
	v_mul_f32_e32 v35, 0xbfb8aa3b, v13
	v_exp_f32_e32 v41, v35
	v_rcp_f32_e32 v35, v1
	v_add_f32_e32 v1, 1.0, v5
	v_rcp_f32_e32 v40, v1
	v_add_f32_e32 v1, 1.0, v41
	v_pk_mul_f32 v[66:67], v[14:15], v[6:7]
	v_lshlrev_b32_e32 v6, 16, v36
	v_rcp_f32_e32 v41, v1
	v_and_b32_e32 v7, 0xffff0000, v36
	v_mul_f32_e32 v1, 0xbfb8aa3b, v6
	v_exp_f32_e32 v1, v1
	v_mul_f32_e32 v5, 0xbfb8aa3b, v7
	v_exp_f32_e32 v5, v5
	v_pk_mul_f32 v[68:69], v[32:33], v[8:9]
	v_lshlrev_b32_e32 v8, 16, v37
	v_add_f32_e32 v1, 1.0, v1
	v_and_b32_e32 v9, 0xffff0000, v37
	v_rcp_f32_e32 v14, v1
	v_add_f32_e32 v1, 1.0, v5
	v_mul_f32_e32 v5, 0xbfb8aa3b, v8
	v_exp_f32_e32 v5, v5
	v_mul_f32_e32 v15, 0xbfb8aa3b, v9
	v_exp_f32_e32 v33, v15
	v_pk_mul_f32 v[70:71], v[34:35], v[10:11]
	v_lshlrev_b32_e32 v10, 16, v38
	v_and_b32_e32 v11, 0xffff0000, v38
	v_rcp_f32_e32 v15, v1
	v_add_f32_e32 v1, 1.0, v5
	v_mul_f32_e32 v5, 0xbfb8aa3b, v10
	v_rcp_f32_e32 v32, v1
	v_add_f32_e32 v1, 1.0, v33
	v_exp_f32_e32 v5, v5
	v_mul_f32_e32 v33, 0xbfb8aa3b, v11
	v_exp_f32_e32 v35, v33
	v_pk_mul_f32 v[72:73], v[40:41], v[12:13]
	v_lshlrev_b32_e32 v12, 16, v39
	v_and_b32_e32 v13, 0xffff0000, v39
	v_rcp_f32_e32 v33, v1
	v_add_f32_e32 v1, 1.0, v5
	v_mul_f32_e32 v5, 0xbfb8aa3b, v12
	v_rcp_f32_e32 v34, v1
	v_add_f32_e32 v1, 1.0, v35
	v_exp_f32_e32 v5, v5
	v_mul_f32_e32 v35, 0xbfb8aa3b, v13
; template <int TYPE>
; __device__ __forceinline__ void pass3_item(const KArgs& a, int l, int item, LAS unsigned char* lds) {
;     ...
;     f32x4 o[4];
; #pragma unroll
;     for (int it = 0; it < 4; ++it) o[it] = (f32x4){0.f, 0.f, 0.f, 0.f};
; #pragma unroll 1
;     for (int dir = 0; dir < 2; ++dir) {
;         const int sitem = ((b * 4 + h) * 2 + dir) * NCH + c;
;         const bf16_t* ST = (const bf16_t*)(wsb + (TYPE ? WS_SH : WS_SG)) + (size_t)sitem * 128 * DK + (size_t)(wid * 16 + fr) * DK + fq * 8;
;         bf16x8 sf[DK / 32];
; #pragma unroll
;         for (int ks = 0; ks < DK / 32; ++ks) sf[ks] = *(const bf16x8*)(ST + ks * 32);
;         if (dir) __syncthreads();
;         { LgRaw rw; rw.a0 = dir ? raw1.a0 : raw0.a0; rw.a1 = dir ? raw1.a1 : raw0.a1; rw.k = dir ? raw1.k : raw0.k; lg_compute<TYPE>(a, wsb, l, h, dir, rw, lds, tid); }
;         cumsum_g<TYPE>(dir, lds, tid);
; #pragma unroll
;         for (int e2 = 0; e2 < DK / 64; ++e2) { const int task = tid + 512 * e2, i = task / C::ND8, d8 = task % C::ND8;
;             const f32x4 g0 = *(LAS f32x4*)(G + i * C::LDG + d8 * 8), g1 = *(LAS f32x4*)(G + i * C::LDG + d8 * 8 + 4);
;             const f32x4 m0 = *(LAS f32x4*)(G + 32 * C::LDG + d8 * 8), m1 = *(LAS f32x4*)(G + 32 * C::LDG + d8 * 8 + 4);
;             float kk[8], qq[8], qt[8], qg[8]; unpack8(*(LAS bf16x8*)(Kb + i * C::LDK_ + d8 * 8), kk);
; #pragma unroll
;             for (int e = 0; e < 8; ++e) qq[e] = qf[e2][e];
; #pragma unroll
;             for (int e = 0; e < 8; ++e) { const float gg = e < 4 ? g0[e] : g1[e - 4], gm = e < 4 ? m0[e] : m1[e - 4];
;                 const float q = qq[e];
;                 qt[e] = q * __expf(gg - gm); qg[e] = q * __expf(gg); kk[e] = kk[e] * __expf(gm - gg); }
;             *(LAS bf16x8*)(QT + i * C::LDK_ + d8 * 8) = pack8(qt); *(LAS bf16x8*)(QG + i * C::LDK_ + d8 * 8) = pack8(qg); *(LAS bf16x8*)(Kb + i * C::LDK_ + d8 * 8) = pack8(kk); }
;         __syncthreads();
;         { const int it = wid >> 1;
; #pragma unroll
;           for (int jj = 0; jj < 2; ++jj) { const int jt = 2 * (wid & 1) + jj;
;             f32x4 acc = {0.f, 0.f, 0.f, 0.f};
; #pragma unroll
;             for (int ks = 0; ks < DK / 32; ++ks) {
;                 const bf16x8 af = *(LAS bf16x8*)(QT + (it * 16 + fr) * C::LDK_ + ks * 32 + fq * 8), bfr = *(LAS bf16x8*)(Kb + (jt * 16 + fr) * C::LDK_ + ks * 32 + fq * 8);
	v_exp_f32_e32 v37, v35
	v_rcp_f32_e32 v35, v1
	v_add_f32_e32 v1, 1.0, v5
	v_pk_mul_f32 v[74:75], v[14:15], v[6:7]
	v_or_b32_e32 v6, v64, v89
	v_rcp_f32_e32 v36, v1
	v_add_f32_e32 v1, 1.0, v37
	v_ashrrev_i32_e32 v7, 31, v6
	v_rcp_f32_e32 v37, v1
	v_pk_mul_f32 v[76:77], v[32:33], v[8:9]
	v_bfe_u32 v1, v65, 4, 2
	v_lshlrev_b64 v[8:9], 8, v[6:7]
	v_lshl_add_u64 v[8:9], s[58:59], 0, v[8:9]
	v_lshlrev_b32_e32 v82, 4, v1
	s_or_b32 s70, s7, s6
	v_lshl_add_u64 v[8:9], v[8:9], 0, v[82:83]
	s_mov_b64 s[6:7], 0x35700000
	v_lshl_add_u64 v[84:85], v[8:9], 0, s[6:7]
	s_lshl_b32 s6, s8, 9
	s_add_u32 s6, s58, s6
	s_addc_u32 s7, s59, 0
	v_lshlrev_b32_e32 v8, 2, v42
	v_mov_b32_e32 v9, v113
	v_pk_mul_f32 v[78:79], v[34:35], v[10:11]
	v_lshl_add_u64 v[10:11], s[6:7], 0, v[8:9]
	s_mov_b64 s[6:7], 0x3e200000
	s_movk_i32 s22, 0x110
	v_lshl_add_u64 v[86:87], v[10:11], 0, s[6:7]
	v_mul_lo_u32 v9, v0, s91
	v_mul_lo_u32 v10, v0, s22
	v_lshrrev_b32_e32 v0, 25, v43
	v_add_u32_e32 v0, v65, v0
	v_ashrrev_i32_e32 v11, 7, v0
	v_and_b32_e32 v0, 0x3fffff80, v0
	v_sub_u32_e32 v0, v65, v0
	v_lshlrev_b32_e32 v0, 2, v0
	v_add_u32_e32 v88, 0, v0
	v_add_u32_e32 v106, s74, v0
	v_ashrrev_i32_e32 v0, 3, v65
	v_pk_mul_f32 v[80:81], v[36:37], v[12:13]
	s_movk_i32 s0, 0xff81
	v_and_b32_e32 v12, -16, v0
	v_bfi_b32 v13, -16, v0, v65
	v_add_u32_e32 v0, 0, v82
	v_lshlrev_b32_e32 v83, 2, v1
	v_lshlrev_b32_e32 v5, 3, v1
	v_cmp_gt_i32_e64 s[6:7], s0, v65
	s_movk_i32 s0, 0x7f
	v_mad_u64_u32 v[90:91], s[20:21], v13, s22, v[0:1]
	v_or_b32_e32 v1, v83, v12
	v_mul_lo_u32 v12, v6, s3
	v_cmp_lt_i32_e64 s[64:65], s0, v65
	s_movk_i32 s0, 0x17f
	v_add_u32_e32 v12, s95, v12
	v_bitop3_b32 v13, v64, 56, v89 bitop3:0xc8
	v_bitop3_b32 v6, v6, v5, 56 bitop3:0x6c
	v_cmp_lt_i32_e64 s[14:15], s0, v65
	s_movk_i32 s0, 0x180
	v_lshl_add_u32 v91, v6, 1, v12
	v_bitop3_b32 v5, v5, v13, 32 bitop3:0x36
	v_mul_lo_u32 v6, v2, s91
	v_cmp_gt_i32_e64 s[16:17], s0, v65
	s_movk_i32 s0, 0x1ff
	v_lshl_add_u32 v107, v5, 1, v12
	v_add_u32_e32 v6, 0, v6
	v_lshlrev_b32_e32 v12, 5, v44
	v_cmp_lt_i32_e64 s[18:19], s0, v65
	s_movk_i32 s0, 0x2100
	v_add_u32_e32 v108, v6, v12
	v_add_u32_e32 v109, 0, v12
	v_lshlrev_b32_e32 v12, 8, v2
	v_lshlrev_b32_e32 v105, 4, v11
	v_mul_lo_u32 v11, v11, s0
	v_readlane_b32 s0, v255, 8
	v_sub_u32_e32 v6, v6, v12
	v_lshlrev_b32_e32 v12, 4, v44
	v_mul_lo_u32 v2, v2, s22
	v_add3_u32 v111, s0, v2, v12
	v_mul_lo_u32 v2, v4, s91
	v_add_u32_e32 v7, 0, v8
	v_add_u32_e32 v110, v6, v12
	v_add_u32_e32 v2, 0, v2
	v_lshlrev_b32_e32 v6, 5, v45
	v_sub_u32_e32 v8, v7, v112
	v_add_u32_e32 v112, v2, v6
	v_add_u32_e32 v114, 0, v6
	v_lshlrev_b32_e32 v6, 8, v4
	v_sub_u32_e32 v2, v2, v6
	v_lshlrev_b32_e32 v6, 4, v45
	v_lshlrev_b32_e32 v3, 5, v3
	v_add_u32_e32 v115, v2, v6
	v_mul_lo_u32 v2, v4, s22
	v_add_u32_e32 v5, s0, v82
	v_add3_u32 v116, s0, v2, v6
	v_and_or_b32 v2, v3, 32, v89
	v_readlane_b32 s0, v255, 9
	v_or_b32_e32 v12, 1, v1
	v_or_b32_e32 v13, 2, v1
	v_or_b32_e32 v14, 3, v1
	v_mul_u32_u24_e32 v3, 0x110, v2
	v_lshl_add_u32 v4, v2, 1, s0
	v_cmp_ge_i32_e64 s[20:21], v2, v1
	v_cmp_le_i32_e64 s[22:23], v2, v1
	v_cmp_gt_i32_e64 s[24:25], v2, v1
	v_cmp_le_i32_e64 s[26:27], v2, v12
	v_cmp_ge_i32_e64 s[28:29], v2, v13
	v_cmp_le_i32_e64 s[30:31], v2, v13
	v_cmp_ge_i32_e64 s[34:35], v2, v14
	v_cmp_le_i32_e64 s[36:37], v2, v14
	v_or_b32_e32 v2, 16, v2
	v_mul_lo_u32 v6, v1, s3
	v_cmp_ge_i32_e64 s[38:39], v2, v1
	v_cmp_le_i32_e64 s[40:41], v2, v1
	v_lshlrev_b32_e32 v15, 1, v2
	v_cmp_gt_i32_e64 s[42:43], v2, v1
	v_mul_u32_u24_e32 v1, 0x90, v89
	s_movk_i32 s10, 0xff
	v_add3_u32 v117, s0, v6, v15
	v_cmp_le_i32_e64 s[44:45], v2, v12
	v_add3_u32 v121, s0, v1, v82
	v_mul_u32_u24_e32 v1, 0x110, v89
	v_mov_b32_e32 v12, 0
	v_lshl_add_u32 v104, v65, 2, s74
	v_cmp_gt_i32_e64 s[8:9], s66, v65
	v_cmp_lt_i32_e64 s[10:11], s10, v65
	v_cmp_gt_i32_e64 s[12:13], s67, v65
	v_add_u32_e32 v118, 0x90, v117
	v_cmp_ge_i32_e64 s[46:47], v2, v13
	v_cmp_le_i32_e64 s[48:49], v2, v13
	v_add_u32_e32 v119, 0x120, v117
	v_cmp_ge_i32_e64 s[50:51], v2, v14
	v_cmp_le_i32_e64 s[52:53], v2, v14
	v_add_u32_e32 v120, 0x1b0, v117
	v_add_u32_e32 v122, 0x900, v121
	v_add_u32_e32 v123, 0x1200, v121
	v_add_u32_e32 v124, 0x1b00, v121
	s_mov_b32 s54, 0
	s_mov_b64 s[66:67], -1
	v_add_u32_e32 v125, v7, v9
	v_add_u32_e32 v126, v8, v10
	v_add_u32_e32 v127, v88, v11
	v_add_u32_e32 v128, v0, v3
	v_add_u32_e32 v129, v4, v6
	v_add_u32_e32 v130, v5, v1
	v_mov_b32_e32 v13, v12
	v_mov_b32_e32 v14, v12
	v_mov_b32_e32 v15, v12
	v_mov_b32_e32 v8, v12
	v_mov_b32_e32 v9, v12
	v_mov_b32_e32 v10, v12
	v_mov_b32_e32 v11, v12
	v_mov_b32_e32 v4, v12
	v_mov_b32_e32 v5, v12
	v_mov_b32_e32 v6, v12
	v_mov_b32_e32 v7, v12
	v_mov_b32_e32 v0, v12
	v_mov_b32_e32 v1, v12
	v_mov_b32_e32 v2, v12
	v_mov_b32_e32 v3, v12
	s_branch .LBB0_495

; __device__ __forceinline__ float bf2f(unsigned v) { return __uint_as_float(v << 16); }
; template <int TYPE>
; __device__ __forceinline__ void pass3_item(const KArgs& a, int l, int item, LAS unsigned char* lds) {
;     ...
;     const float gain = ((const float*)a.in[TYPE ? 7 : 5])[l * 128 + wid * 16 + fr];
;     bf16_t* mix = (bf16_t*)(wsb + WS_XN);
;     float gtv[4][4];
; #pragma unroll
;     for (int it = 0; it < 4; ++it)
; #pragma unroll
;         for (int r = 0; r < 4; ++r) gtv[it][r] = bf2f(u[(tok0 + it * 16 + fq * 4 + r) * DINP + (TYPE ? C_HG : C_GG) + h * 128 + wid * 16 + fr]);
.LBB0_509:
	s_or_b64 exec, exec, s[8:9]
	v_readlane_b32 s4, v255, 29
	v_readlane_b32 s40, v253, 48
	v_readlane_b32 s50, v253, 58
	v_add_u32_e32 v12, s4, v52
	v_or_b32_e32 v12, v12, v67
	v_ashrrev_i32_e32 v13, 31, v12
	v_readlane_b32 s51, v253, 59
	v_readlane_b32 s6, v255, 31
	v_readlane_b32 s8, v255, 33
	v_lshl_add_u64 v[12:13], v[12:13], 2, s[50:51]
	v_readlane_b32 s7, v255, 32
	s_waitcnt lgkmcnt(0)
	s_barrier
	global_load_dword v54, v[12:13], off
	v_or_b32_e32 v12, s8, v63
	v_mov_b64_e32 v[50:51], s[6:7]
	s_movk_i32 s2, 0x2a00
	v_readlane_b32 s9, v255, 34
	v_mad_u64_u32 v[14:15], s[6:7], v12, s2, v[50:51]
	s_mul_i32 s4, s9, 0x2a00
	v_readlane_b32 s6, v255, 35
	v_ashrrev_i32_e32 v53, 31, v52
	v_add_u32_e32 v15, s4, v15
	s_lshl_b32 s72, s6, 1
	v_lshl_add_u64 v[14:15], v[14:15], 0, s[72:73]
	v_lshlrev_b64 v[24:25], 1, v[52:53]
	v_lshl_add_u64 v[14:15], v[14:15], 0, v[24:25]
	v_lshlrev_b32_e32 v112, 1, v67
	v_lshl_add_u64 v[14:15], v[14:15], 0, v[112:113]
	global_load_ushort v142, v[14:15], off offset:2112
	v_readlane_b32 s7, v255, 36
	v_or_b32_e32 v46, 2, v12
	v_or_b32_e32 v48, 3, v12
	v_or_b32_e32 v67, 16, v63
	v_or_b32_e32 v44, s8, v67
	v_or_b32_e32 v42, 17, v12
	v_or_b32_e32 v40, 18, v12
	v_or_b32_e32 v28, 19, v12
	v_or_b32_e32 v60, 32, v63
	v_or_b32_e32 v26, s8, v60
	v_or_b32_e32 v30, 33, v12
	v_or_b32_e32 v36, 34, v12
	v_or_b32_e32 v38, 35, v12
	v_or_b32_e32 v56, 48, v63
	v_or_b32_e32 v22, s8, v56
	v_or_b32_e32 v20, 49, v12
	v_or_b32_e32 v18, 50, v12
	v_readlane_b32 s74, v255, 20
	v_mov_b32_e32 v13, s9
	v_mov_b32_e32 v15, s9
	v_mov_b32_e32 v47, s9
	v_mov_b32_e32 v49, s9
	v_mov_b32_e32 v45, s9
	v_mov_b32_e32 v43, s9
	v_mov_b32_e32 v41, s9
	v_mov_b32_e32 v29, s9
	v_mov_b32_e32 v27, s9
	v_mov_b32_e32 v31, s9
	v_mov_b32_e32 v37, s9
	v_mov_b32_e32 v39, s9
	v_mov_b32_e32 v23, s9
	v_mov_b32_e32 v21, s9
	v_mov_b32_e32 v19, s9
	v_readlane_b32 s68, v255, 16
	v_readlane_b32 s70, v255, 18
	v_readlane_b32 s41, v253, 49
	v_readlane_b32 s46, v253, 54
	v_readlane_b32 s47, v253, 55
	v_readlane_b32 s48, v253, 56
	v_readlane_b32 s49, v253, 57
	v_readlane_b32 s54, v253, 62
	v_readlane_b32 s55, v253, 63
	v_readlane_b32 s69, v255, 17
	v_readlane_b32 s71, v255, 19
	s_movk_i32 s66, 0x80
	s_movk_i32 s67, 0x100
	s_movk_i32 s3, 0x90
	v_readlane_b32 s42, v253, 50
	v_readlane_b32 s43, v253, 51
	v_readlane_b32 s44, v253, 52
	v_readlane_b32 s45, v253, 53
	v_readlane_b32 s52, v253, 60
	v_readlane_b32 s53, v253, 61


; __device__ __forceinline__ float bf2f(unsigned v) { return __uint_as_float(v << 16); }
; template <int TYPE>
; __device__ __forceinline__ void pass3_item(const KArgs& a, int l, int item, LAS unsigned char* lds) {
;     ...
;         for (int r = 0; r < 4; ++r) gtv[it][r] = bf2f(u[(tok0 + it * 16 + fq * 4 + r) * DINP + (TYPE ? C_HG : C_GG) + h * 128 + wid * 16 + fr]);
	v_or_b32_e32 v14, 1, v12
	v_mad_u64_u32 v[16:17], s[6:7], v14, s2, v[50:51]
	v_add_u32_e32 v17, s4, v17
	v_lshl_add_u64 v[16:17], v[16:17], 0, s[72:73]
	v_lshl_add_u64 v[16:17], v[16:17], 0, v[24:25]
	v_lshl_add_u64 v[16:17], v[16:17], 0, v[112:113]
	global_load_ushort v143, v[16:17], off offset:2112


; __device__ __forceinline__ float bf2f(unsigned v) { return __uint_as_float(v << 16); }
; template <int TYPE>
; __device__ __forceinline__ void pass3_item(const KArgs& a, int l, int item, LAS unsigned char* lds) {
;     ...
;         for (int r = 0; r < 4; ++r) gtv[it][r] = bf2f(u[(tok0 + it * 16 + fq * 4 + r) * DINP + (TYPE ? C_HG : C_GG) + h * 128 + wid * 16 + fr]);
	v_mad_u64_u32 v[16:17], s[6:7], v46, s2, v[50:51]
	v_add_u32_e32 v17, s4, v17
	v_lshl_add_u64 v[16:17], v[16:17], 0, s[72:73]
	v_lshl_add_u64 v[16:17], v[16:17], 0, v[24:25]
	v_lshl_add_u64 v[16:17], v[16:17], 0, v[112:113]
	global_load_ushort v144, v[16:17], off offset:2112


; __device__ __forceinline__ float bf2f(unsigned v) { return __uint_as_float(v << 16); }
; template <int TYPE>
; __device__ __forceinline__ void pass3_item(const KArgs& a, int l, int item, LAS unsigned char* lds) {
;     ...
;         for (int r = 0; r < 4; ++r) gtv[it][r] = bf2f(u[(tok0 + it * 16 + fq * 4 + r) * DINP + (TYPE ? C_HG : C_GG) + h * 128 + wid * 16 + fr]);
	v_mad_u64_u32 v[16:17], s[6:7], v48, s2, v[50:51]
	v_add_u32_e32 v17, s4, v17
	v_lshl_add_u64 v[16:17], v[16:17], 0, s[72:73]
	v_lshl_add_u64 v[16:17], v[16:17], 0, v[24:25]
	v_lshl_add_u64 v[16:17], v[16:17], 0, v[112:113]
	global_load_ushort v145, v[16:17], off offset:2112


; __device__ __forceinline__ float bf2f(unsigned v) { return __uint_as_float(v << 16); }
; template <int TYPE>
; __device__ __forceinline__ void pass3_item(const KArgs& a, int l, int item, LAS unsigned char* lds) {
;     ...
;         for (int r = 0; r < 4; ++r) gtv[it][r] = bf2f(u[(tok0 + it * 16 + fq * 4 + r) * DINP + (TYPE ? C_HG : C_GG) + h * 128 + wid * 16 + fr]);
	v_mad_u64_u32 v[16:17], s[6:7], v44, s2, v[50:51]
	v_add_u32_e32 v17, s4, v17
	v_lshl_add_u64 v[16:17], v[16:17], 0, s[72:73]
	v_lshl_add_u64 v[16:17], v[16:17], 0, v[24:25]
	v_lshl_add_u64 v[16:17], v[16:17], 0, v[112:113]
	global_load_ushort v146, v[16:17], off offset:2112


; __device__ __forceinline__ float bf2f(unsigned v) { return __uint_as_float(v << 16); }
; template <int TYPE>
; __device__ __forceinline__ void pass3_item(const KArgs& a, int l, int item, LAS unsigned char* lds) {
;     ...
;         for (int r = 0; r < 4; ++r) gtv[it][r] = bf2f(u[(tok0 + it * 16 + fq * 4 + r) * DINP + (TYPE ? C_HG : C_GG) + h * 128 + wid * 16 + fr]);
	v_mad_u64_u32 v[16:17], s[6:7], v42, s2, v[50:51]
	v_add_u32_e32 v17, s4, v17
	v_lshl_add_u64 v[16:17], v[16:17], 0, s[72:73]
	v_lshl_add_u64 v[16:17], v[16:17], 0, v[24:25]
	v_lshl_add_u64 v[16:17], v[16:17], 0, v[112:113]
	global_load_ushort v147, v[16:17], off offset:2112


; __device__ __forceinline__ float bf2f(unsigned v) { return __uint_as_float(v << 16); }
; template <int TYPE>
; __device__ __forceinline__ void pass3_item(const KArgs& a, int l, int item, LAS unsigned char* lds) {
;     ...
;         for (int r = 0; r < 4; ++r) gtv[it][r] = bf2f(u[(tok0 + it * 16 + fq * 4 + r) * DINP + (TYPE ? C_HG : C_GG) + h * 128 + wid * 16 + fr]);
	v_mad_u64_u32 v[16:17], s[6:7], v40, s2, v[50:51]
	v_add_u32_e32 v17, s4, v17
	v_lshl_add_u64 v[16:17], v[16:17], 0, s[72:73]
	v_lshl_add_u64 v[16:17], v[16:17], 0, v[24:25]
	v_lshl_add_u64 v[16:17], v[16:17], 0, v[112:113]
	global_load_ushort v148, v[16:17], off offset:2112


; __device__ __forceinline__ float bf2f(unsigned v) { return __uint_as_float(v << 16); }
; template <int TYPE>
; __device__ __forceinline__ void pass3_item(const KArgs& a, int l, int item, LAS unsigned char* lds) {
;     ...
;         for (int r = 0; r < 4; ++r) gtv[it][r] = bf2f(u[(tok0 + it * 16 + fq * 4 + r) * DINP + (TYPE ? C_HG : C_GG) + h * 128 + wid * 16 + fr]);
	v_mad_u64_u32 v[16:17], s[6:7], v28, s2, v[50:51]
	v_add_u32_e32 v17, s4, v17
	v_lshl_add_u64 v[16:17], v[16:17], 0, s[72:73]
	v_lshl_add_u64 v[16:17], v[16:17], 0, v[24:25]
	v_lshl_add_u64 v[16:17], v[16:17], 0, v[112:113]
	global_load_ushort v149, v[16:17], off offset:2112


; __device__ __forceinline__ float bf2f(unsigned v) { return __uint_as_float(v << 16); }
; template <int TYPE>
; __device__ __forceinline__ void pass3_item(const KArgs& a, int l, int item, LAS unsigned char* lds) {
;     ...
;         for (int r = 0; r < 4; ++r) gtv[it][r] = bf2f(u[(tok0 + it * 16 + fq * 4 + r) * DINP + (TYPE ? C_HG : C_GG) + h * 128 + wid * 16 + fr]);
	v_mad_u64_u32 v[16:17], s[6:7], v26, s2, v[50:51]
	v_add_u32_e32 v17, s4, v17
	v_lshl_add_u64 v[16:17], v[16:17], 0, s[72:73]
	v_lshl_add_u64 v[16:17], v[16:17], 0, v[24:25]
	v_lshl_add_u64 v[16:17], v[16:17], 0, v[112:113]
	global_load_ushort v150, v[16:17], off offset:2112


; __device__ __forceinline__ float bf2f(unsigned v) { return __uint_as_float(v << 16); }
; template <int TYPE>
; __device__ __forceinline__ void pass3_item(const KArgs& a, int l, int item, LAS unsigned char* lds) {
;     ...
;         for (int r = 0; r < 4; ++r) gtv[it][r] = bf2f(u[(tok0 + it * 16 + fq * 4 + r) * DINP + (TYPE ? C_HG : C_GG) + h * 128 + wid * 16 + fr]);
	v_mad_u64_u32 v[16:17], s[6:7], v30, s2, v[50:51]
	v_add_u32_e32 v17, s4, v17
	v_lshl_add_u64 v[16:17], v[16:17], 0, s[72:73]
	v_lshl_add_u64 v[16:17], v[16:17], 0, v[24:25]
	v_lshl_add_u64 v[16:17], v[16:17], 0, v[112:113]
	global_load_ushort v151, v[16:17], off offset:2112


; __device__ __forceinline__ float bf2f(unsigned v) { return __uint_as_float(v << 16); }
; template <int TYPE>
; __device__ __forceinline__ void pass3_item(const KArgs& a, int l, int item, LAS unsigned char* lds) {
;     ...
;         for (int r = 0; r < 4; ++r) gtv[it][r] = bf2f(u[(tok0 + it * 16 + fq * 4 + r) * DINP + (TYPE ? C_HG : C_GG) + h * 128 + wid * 16 + fr]);
	v_mad_u64_u32 v[16:17], s[6:7], v36, s2, v[50:51]
	v_add_u32_e32 v17, s4, v17
	v_lshl_add_u64 v[16:17], v[16:17], 0, s[72:73]
	v_lshl_add_u64 v[16:17], v[16:17], 0, v[24:25]
	v_lshl_add_u64 v[16:17], v[16:17], 0, v[112:113]
	global_load_ushort v152, v[16:17], off offset:2112


; __device__ __forceinline__ float bf2f(unsigned v) { return __uint_as_float(v << 16); }
; template <int TYPE>
; __device__ __forceinline__ void pass3_item(const KArgs& a, int l, int item, LAS unsigned char* lds) {
;     ...
;         for (int r = 0; r < 4; ++r) gtv[it][r] = bf2f(u[(tok0 + it * 16 + fq * 4 + r) * DINP + (TYPE ? C_HG : C_GG) + h * 128 + wid * 16 + fr]);
	v_mad_u64_u32 v[16:17], s[6:7], v38, s2, v[50:51]
	v_add_u32_e32 v17, s4, v17
	v_lshl_add_u64 v[16:17], v[16:17], 0, s[72:73]
	v_lshl_add_u64 v[16:17], v[16:17], 0, v[24:25]
	v_lshl_add_u64 v[16:17], v[16:17], 0, v[112:113]
	global_load_ushort v153, v[16:17], off offset:2112


; __device__ __forceinline__ float bf2f(unsigned v) { return __uint_as_float(v << 16); }
; template <int TYPE>
; __device__ __forceinline__ void pass3_item(const KArgs& a, int l, int item, LAS unsigned char* lds) {
;     ...
;         for (int r = 0; r < 4; ++r) gtv[it][r] = bf2f(u[(tok0 + it * 16 + fq * 4 + r) * DINP + (TYPE ? C_HG : C_GG) + h * 128 + wid * 16 + fr]);
	v_mad_u64_u32 v[16:17], s[6:7], v22, s2, v[50:51]
	v_add_u32_e32 v17, s4, v17
	v_lshl_add_u64 v[16:17], v[16:17], 0, s[72:73]
	v_lshl_add_u64 v[16:17], v[16:17], 0, v[24:25]
	v_lshl_add_u64 v[16:17], v[16:17], 0, v[112:113]
	global_load_ushort v154, v[16:17], off offset:2112


; __device__ __forceinline__ float bf2f(unsigned v) { return __uint_as_float(v << 16); }
; template <int TYPE>
; __device__ __forceinline__ void pass3_item(const KArgs& a, int l, int item, LAS unsigned char* lds) {
;     ...
;         for (int r = 0; r < 4; ++r) gtv[it][r] = bf2f(u[(tok0 + it * 16 + fq * 4 + r) * DINP + (TYPE ? C_HG : C_GG) + h * 128 + wid * 16 + fr]);
	v_mad_u64_u32 v[16:17], s[6:7], v20, s2, v[50:51]
	v_add_u32_e32 v17, s4, v17
	v_lshl_add_u64 v[16:17], v[16:17], 0, s[72:73]
	v_lshl_add_u64 v[16:17], v[16:17], 0, v[24:25]
	v_lshl_add_u64 v[16:17], v[16:17], 0, v[112:113]
	global_load_ushort v155, v[16:17], off offset:2112


; __device__ __forceinline__ float bf2f(unsigned v) { return __uint_as_float(v << 16); }
; template <int TYPE>
; __device__ __forceinline__ void pass3_item(const KArgs& a, int l, int item, LAS unsigned char* lds) {
;     ...
;         for (int r = 0; r < 4; ++r) gtv[it][r] = bf2f(u[(tok0 + it * 16 + fq * 4 + r) * DINP + (TYPE ? C_HG : C_GG) + h * 128 + wid * 16 + fr]);
	v_mad_u64_u32 v[16:17], s[6:7], v18, s2, v[50:51]
	v_add_u32_e32 v17, s4, v17
	v_lshl_add_u64 v[16:17], v[16:17], 0, s[72:73]
	v_lshl_add_u64 v[16:17], v[16:17], 0, v[24:25]
	v_lshl_add_u64 v[16:17], v[16:17], 0, v[112:113]
	global_load_ushort v156, v[16:17], off offset:2112
	v_mov_b32_e32 v17, s9

; __device__ __forceinline__ unsigned f2bf(float f) { unsigned u = __float_as_uint(f); return (u + 0x7fffu + ((u >> 16) & 1u)) >> 16; }
; __device__ __forceinline__ float silu_(float z) { return z * sigmoid_(z); }
; template <int TYPE>
; __device__ __forceinline__ void pass3_item(const KArgs& a, int l, int item, LAS unsigned char* lds) {
;     ...
; #pragma unroll
;     for (int it = 0; it < 4; ++it)
; #pragma unroll
;         for (int r = 0; r < 4; ++r) { const int i = it * 16 + fq * 4 + r;
;             const float rstd = RSTD[i];
;             const float gt = gtv[it][r];
;             const float yv = o[it][r] * rstd * gain * silu_(gt);
;             mix[(tok0 + i) * DM + (TYPE ? 512 : 0) + h * 128 + wid * 16 + fr] = (bf16_t)f2bf(yv); }
	s_waitcnt vmcnt(0) lgkmcnt(0)
	v_lshlrev_b32_e32 v68, 16, v142
	v_lshlrev_b32_e32 v69, 16, v143
	v_lshlrev_b32_e32 v70, 16, v144
	v_lshlrev_b32_e32 v71, 16, v145
	v_lshlrev_b32_e32 v66, 16, v146
	v_lshlrev_b32_e32 v65, 16, v147
	v_lshlrev_b32_e32 v64, 16, v148
	v_lshlrev_b32_e32 v61, 16, v149
	v_lshlrev_b32_e32 v57, 16, v150
	v_lshlrev_b32_e32 v58, 16, v151
	v_lshlrev_b32_e32 v59, 16, v152
	v_lshlrev_b32_e32 v62, 16, v153
	v_lshlrev_b32_e32 v55, 16, v154
	v_lshlrev_b32_e32 v53, 16, v155
	v_lshlrev_b32_e32 v52, 16, v156
	v_or_b32_e32 v16, 51, v12
	v_mad_u64_u32 v[50:51], s[6:7], v16, s2, v[50:51]
	v_add_u32_e32 v51, s4, v51
	v_lshl_add_u64 v[50:51], v[50:51], 0, s[72:73]
	v_lshl_add_u64 v[50:51], v[50:51], 0, v[24:25]
	v_lshl_add_u64 v[50:51], v[50:51], 0, v[112:113]
	global_load_ushort v50, v[50:51], off offset:2112
	v_lshl_add_u32 v51, v63, 2, s74
	ds_read_b128 v[72:75], v51
	v_mul_f32_e32 v51, 0xbfb8aa3b, v68
	v_exp_f32_e32 v51, v51
	v_readlane_b32 s6, v255, 37
	v_readlane_b32 s7, v255, 38
	s_add_u32 s6, s6, s72
	v_add_f32_e32 v51, 1.0, v51
	v_rcp_f32_e32 v51, v51
	s_addc_u32 s7, s7, 0
	s_waitcnt lgkmcnt(0)
	v_mul_f32_e32 v32, v32, v72
	v_lshl_add_u64 v[24:25], s[6:7], 0, v[24:25]
	v_mul_f32_e32 v32, v54, v32
	v_mul_f32_e32 v51, v51, v68
	v_lshl_add_u64 v[24:25], v[24:25], 0, v[112:113]
	s_mov_b64 s[6:7], 0x6300000
	v_mul_f32_e32 v32, v51, v32
	v_lshl_add_u64 v[24:25], v[24:25], 0, s[6:7]
	v_bfe_u32 v51, v32, 16, 1
	v_lshlrev_b64 v[12:13], 12, v[12:13]
	v_add3_u32 v32, v32, v51, s1
	v_lshl_add_u64 v[12:13], v[24:25], 0, v[12:13]
	global_store_short_d16_hi v[12:13], v32, off
	v_mul_f32_e32 v13, 0xbfb8aa3b, v69
	v_exp_f32_e32 v13, v13
	v_mul_f32_e32 v12, v33, v73
	v_mul_f32_e32 v12, v54, v12
	v_readlane_b32 s4, v255, 30
	v_add_f32_e32 v13, 1.0, v13
	v_rcp_f32_e32 v13, v13
	s_add_i32 s4, s4, s70
	s_cmpk_gt_i32 s4, 0x7ff
	v_mul_f32_e32 v13, v13, v69
	v_mul_f32_e32 v12, v13, v12
	v_bfe_u32 v13, v12, 16, 1
	v_add3_u32 v32, v12, v13, s1
	v_lshlrev_b64 v[12:13], 12, v[14:15]
	v_lshl_add_u64 v[12:13], v[24:25], 0, v[12:13]
	global_store_short_d16_hi v[12:13], v32, off
	v_mul_f32_e32 v13, 0xbfb8aa3b, v70
	v_exp_f32_e32 v13, v13
	v_mul_f32_e32 v12, v34, v74
	v_mul_f32_e32 v12, v54, v12
	v_lshlrev_b64 v[32:33], 12, v[44:45]
	v_add_f32_e32 v13, 1.0, v13
	v_rcp_f32_e32 v13, v13
	v_lshl_add_u64 v[32:33], v[24:25], 0, v[32:33]
	v_mul_f32_e32 v13, v13, v70
	v_mul_f32_e32 v12, v13, v12
	v_bfe_u32 v13, v12, 16, 1
	v_add3_u32 v14, v12, v13, s1
	v_lshlrev_b64 v[12:13], 12, v[46:47]
	v_lshl_add_u64 v[12:13], v[24:25], 0, v[12:13]
	global_store_short_d16_hi v[12:13], v14, off
	v_mul_f32_e32 v13, 0xbfb8aa3b, v71
	v_exp_f32_e32 v13, v13
	v_mul_f32_e32 v12, v35, v75
	v_mul_f32_e32 v12, v54, v12
	v_add_f32_e32 v13, 1.0, v13
	v_rcp_f32_e32 v13, v13
	s_waitcnt vmcnt(0)
	v_lshlrev_b32_e32 v50, 16, v50
	v_mul_f32_e32 v13, v13, v71
	v_mul_f32_e32 v12, v13, v12
	v_bfe_u32 v13, v12, 16, 1
	v_add3_u32 v14, v12, v13, s1
	v_lshlrev_b64 v[12:13], 12, v[48:49]
	v_lshl_add_u64 v[12:13], v[24:25], 0, v[12:13]
	global_store_short_d16_hi v[12:13], v14, off
	v_lshl_add_u32 v12, v67, 2, s74
	ds_read_b128 v[12:15], v12
	s_waitcnt lgkmcnt(0)
	v_mul_f32_e32 v8, v8, v12
	v_mul_f32_e32 v12, 0xbfb8aa3b, v66
	v_exp_f32_e32 v12, v12
	v_mul_f32_e32 v8, v54, v8
	v_add_f32_e32 v12, 1.0, v12
	v_rcp_f32_e32 v12, v12
	s_nop 0
	v_mul_f32_e32 v12, v12, v66
	v_mul_f32_e32 v8, v12, v8
	v_bfe_u32 v12, v8, 16, 1
	v_add3_u32 v8, v8, v12, s1
	global_store_short_d16_hi v[32:33], v8, off
	v_mul_f32_e32 v8, v9, v13
	v_mul_f32_e32 v9, 0xbfb8aa3b, v65
	v_exp_f32_e32 v9, v9
	v_mul_f32_e32 v8, v54, v8
	v_add_f32_e32 v9, 1.0, v9
	v_rcp_f32_e32 v9, v9
	s_nop 0
	v_mul_f32_e32 v9, v9, v65
	v_mul_f32_e32 v8, v9, v8
	v_bfe_u32 v9, v8, 16, 1
	v_add3_u32 v12, v8, v9, s1
	v_lshlrev_b64 v[8:9], 12, v[42:43]
	v_lshl_add_u64 v[8:9], v[24:25], 0, v[8:9]
	global_store_short_d16_hi v[8:9], v12, off
	v_mul_f32_e32 v9, 0xbfb8aa3b, v64
	v_exp_f32_e32 v9, v9
	v_mul_f32_e32 v8, v10, v14
	v_mul_f32_e32 v8, v54, v8
	v_lshlrev_b64 v[12:13], 12, v[26:27]
	v_add_f32_e32 v9, 1.0, v9
	v_rcp_f32_e32 v9, v9
	v_lshl_add_u64 v[12:13], v[24:25], 0, v[12:13]
	v_mul_f32_e32 v9, v9, v64
	v_mul_f32_e32 v8, v9, v8
	v_bfe_u32 v9, v8, 16, 1
	v_add3_u32 v10, v8, v9, s1
	v_lshlrev_b64 v[8:9], 12, v[40:41]
	v_lshl_add_u64 v[8:9], v[24:25], 0, v[8:9]
	global_store_short_d16_hi v[8:9], v10, off
	v_mul_f32_e32 v9, 0xbfb8aa3b, v61
	v_exp_f32_e32 v9, v9
	v_mul_f32_e32 v8, v11, v15
	v_mul_f32_e32 v8, v54, v8
	v_add_f32_e32 v9, 1.0, v9
	v_rcp_f32_e32 v9, v9
	s_nop 0
	v_mul_f32_e32 v9, v9, v61
	v_mul_f32_e32 v8, v9, v8
	v_bfe_u32 v9, v8, 16, 1
	v_add3_u32 v10, v8, v9, s1
	v_lshlrev_b64 v[8:9], 12, v[28:29]
	v_lshl_add_u64 v[8:9], v[24:25], 0, v[8:9]
	global_store_short_d16_hi v[8:9], v10, off
	v_lshl_add_u32 v8, v60, 2, s74
	ds_read_b128 v[8:11], v8
	s_waitcnt lgkmcnt(0)
; __device__ __forceinline__ unsigned f2bf(float f) { unsigned u = __float_as_uint(f); return (u + 0x7fffu + ((u >> 16) & 1u)) >> 16; }
; __device__ __forceinline__ float silu_(float z) { return z * sigmoid_(z); }
; template <int TYPE>
; __device__ __forceinline__ void pass3_item(const KArgs& a, int l, int item, LAS unsigned char* lds) {
;     ...
; #pragma unroll
;     for (int it = 0; it < 4; ++it)
; #pragma unroll
;         for (int r = 0; r < 4; ++r) { const int i = it * 16 + fq * 4 + r;
;             const float rstd = RSTD[i];
;             const float gt = gtv[it][r];
;             const float yv = o[it][r] * rstd * gain * silu_(gt);
;             mix[(tok0 + i) * DM + (TYPE ? 512 : 0) + h * 128 + wid * 16 + fr] = (bf16_t)f2bf(yv); }
	v_mul_f32_e32 v4, v4, v8
	v_mul_f32_e32 v8, 0xbfb8aa3b, v57
	v_exp_f32_e32 v8, v8
	v_mul_f32_e32 v4, v54, v4
	v_add_f32_e32 v8, 1.0, v8
	v_rcp_f32_e32 v8, v8
	s_nop 0
	v_mul_f32_e32 v8, v8, v57
	v_mul_f32_e32 v4, v8, v4
	v_bfe_u32 v8, v4, 16, 1
	v_add3_u32 v4, v4, v8, s1
	global_store_short_d16_hi v[12:13], v4, off
	v_mul_f32_e32 v4, v5, v9
	v_mul_f32_e32 v5, 0xbfb8aa3b, v58
	v_exp_f32_e32 v5, v5
	v_mul_f32_e32 v4, v54, v4
	v_add_f32_e32 v5, 1.0, v5
	v_rcp_f32_e32 v5, v5
	s_nop 0
	v_mul_f32_e32 v5, v5, v58
	v_mul_f32_e32 v4, v5, v4
	v_bfe_u32 v5, v4, 16, 1
	v_add3_u32 v8, v4, v5, s1
	v_lshlrev_b64 v[4:5], 12, v[30:31]
	v_lshl_add_u64 v[4:5], v[24:25], 0, v[4:5]
	global_store_short_d16_hi v[4:5], v8, off
	v_mul_f32_e32 v5, 0xbfb8aa3b, v59
	v_exp_f32_e32 v5, v5
	v_mul_f32_e32 v4, v6, v10
	v_mul_f32_e32 v4, v54, v4
	v_lshlrev_b64 v[8:9], 12, v[22:23]
	v_add_f32_e32 v5, 1.0, v5
	v_rcp_f32_e32 v5, v5
	v_lshl_add_u64 v[8:9], v[24:25], 0, v[8:9]
	v_mul_f32_e32 v5, v5, v59
	v_mul_f32_e32 v4, v5, v4
	v_bfe_u32 v5, v4, 16, 1
	v_add3_u32 v6, v4, v5, s1
	v_lshlrev_b64 v[4:5], 12, v[36:37]
	v_lshl_add_u64 v[4:5], v[24:25], 0, v[4:5]
	global_store_short_d16_hi v[4:5], v6, off
	v_mul_f32_e32 v5, 0xbfb8aa3b, v62
	v_exp_f32_e32 v5, v5
	v_mul_f32_e32 v4, v7, v11
	v_mul_f32_e32 v4, v54, v4
	v_add_f32_e32 v5, 1.0, v5
	v_rcp_f32_e32 v5, v5
	s_nop 0
	v_mul_f32_e32 v5, v5, v62
	v_mul_f32_e32 v4, v5, v4
	v_bfe_u32 v5, v4, 16, 1
	v_add3_u32 v6, v4, v5, s1
	v_lshlrev_b64 v[4:5], 12, v[38:39]
	v_lshl_add_u64 v[4:5], v[24:25], 0, v[4:5]
	global_store_short_d16_hi v[4:5], v6, off
	v_lshl_add_u32 v4, v56, 2, s74
	ds_read_b128 v[4:7], v4
	s_waitcnt lgkmcnt(0)
	v_mul_f32_e32 v0, v0, v4
	v_mul_f32_e32 v4, 0xbfb8aa3b, v55
	v_exp_f32_e32 v4, v4
	v_mul_f32_e32 v0, v54, v0
	v_add_f32_e32 v4, 1.0, v4
	v_rcp_f32_e32 v4, v4
	s_nop 0
	v_mul_f32_e32 v4, v4, v55
	v_mul_f32_e32 v0, v4, v0
	v_bfe_u32 v4, v0, 16, 1
	v_add3_u32 v0, v0, v4, s1
	global_store_short_d16_hi v[8:9], v0, off
	v_mul_f32_e32 v0, v1, v5
	v_mul_f32_e32 v1, 0xbfb8aa3b, v53
	v_exp_f32_e32 v1, v1
	v_mul_f32_e32 v0, v54, v0
	v_add_f32_e32 v1, 1.0, v1
	v_rcp_f32_e32 v1, v1
	s_nop 0
	v_mul_f32_e32 v1, v1, v53
	v_mul_f32_e32 v0, v1, v0
	v_bfe_u32 v1, v0, 16, 1
	v_add3_u32 v4, v0, v1, s1
	v_lshlrev_b64 v[0:1], 12, v[20:21]
	v_lshl_add_u64 v[0:1], v[24:25], 0, v[0:1]
	global_store_short_d16_hi v[0:1], v4, off
	v_mul_f32_e32 v1, 0xbfb8aa3b, v52
	v_exp_f32_e32 v1, v1
	v_mul_f32_e32 v0, v2, v6
	v_mul_f32_e32 v0, v54, v0
	v_add_f32_e32 v1, 1.0, v1
	v_rcp_f32_e32 v1, v1
	s_nop 0
	v_mul_f32_e32 v1, v1, v52
	v_mul_f32_e32 v0, v1, v0
	v_bfe_u32 v1, v0, 16, 1
	v_add3_u32 v2, v0, v1, s1
	v_lshlrev_b64 v[0:1], 12, v[18:19]
	v_lshl_add_u64 v[0:1], v[24:25], 0, v[0:1]
	global_store_short_d16_hi v[0:1], v2, off
	v_mul_f32_e32 v1, 0xbfb8aa3b, v50
	v_exp_f32_e32 v1, v1
	v_mul_f32_e32 v0, v3, v7
	v_mul_f32_e32 v0, v54, v0
	v_add_f32_e32 v1, 1.0, v1
	v_rcp_f32_e32 v1, v1
	s_nop 0
	v_mul_f32_e32 v1, v1, v50
	v_mul_f32_e32 v0, v1, v0
	v_bfe_u32 v1, v0, 16, 1
	v_add3_u32 v2, v0, v1, s1
	v_lshlrev_b64 v[0:1], 12, v[16:17]
	v_lshl_add_u64 v[0:1], v[24:25], 0, v[0:1]
	global_store_short_d16_hi v[0:1], v2, off
	v_mov_b32_e32 v250, 0x1f000
	s_mov_b64 s[96:97], exec
	s_mov_b64 exec, s[88:89]
	s_cbranch_execz .Lat_p3g_nw
	ds_write_b32 v250, v249

; #define LAS __attribute__((address_space(3)))
; template <int TYPE>
; __device__ __forceinline__ void pass3_item(const KArgs& a, int l, int item, LAS unsigned char* lds) {
;     ...
;     const int c = item & (NCH - 1), h = (item >> 8) & 3, b = item >> 10;
;     const size_t tok0 = (size_t)b * T + (size_t)c * 64;
;     const bf16_t* u = (const bf16_t*)(wsb + WS_U);
;     const int wid = tid >> 6, lane = tid & 63, fr = lane & 15, fq = lane >> 4;
;     LAS float* G = (LAS float*)(lds + SC_G); LAS bf16_t* Kb = (LAS bf16_t*)(lds + SC_K); LAS bf16_t* QT = (LAS bf16_t*)(lds + SC_QT); LAS bf16_t* QG = (LAS bf16_t*)(lds + SC_QG);
;     LAS bf16_t* VT = (LAS bf16_t*)(lds + SC_VT); LAS bf16_t* P = (LAS bf16_t*)(lds + SC_P); LAS float* RSQ = (LAS float*)(lds + SC_RSQ);
;     const VRaw vr = vT_issue(u + tok0 * DINP + (TYPE ? C_HI : C_GV) + h * 128, tid);
;     bf16x8 qraw[DK / 64];
; #pragma unroll
;     for (int e2 = 0; e2 < DK / 64; ++e2) { const int task = tid + 512 * e2, i = task / C::ND8, d8 = task % C::ND8;
;         qraw[e2] = *(const bf16x8*)(u + (tok0 + i) * DINP + (TYPE ? C_HQ + h * 128 : C_GQ + h * 64) + d8 * 8); }
;     const LgRaw raw0 = lg_issue<TYPE>(u, h, 0, tok0, tid), raw1 = lg_issue<TYPE>(u, h, 1, tok0, tid);
.LBB0_510:
	v_cmp_eq_u32_e64 s[88:89], 0, v195
	s_mov_b64 s[96:97], exec
	v_readlane_b32 s98, v255, 11
	s_nop 1
	s_mov_b64 exec, s[88:89]
	s_cbranch_execz .Lat_p3g_na
	v_mov_b32_e32 v250, s98
	v_lshlrev_b32_e32 v250, 5, v250
	v_add_u32_e32 v250, 0x3e303810, v250
	v_mov_b32_e32 v251, 0
	v_lshl_add_u64 v[250:251], s[68:69], 0, v[250:251]
	v_mov_b32_e32 v249, 1
	global_atomic_add v249, v[250:251], v249, off sc0
.Lat_p3g_na:
	s_mov_b64 exec, s[96:97]
	s_ashr_i32 s6, s4, 10
	s_and_b32 s95, s4, 0xff
	s_ashr_i32 s7, s6, 31
	s_bfe_u32 s8, s4, 0x20008
	v_writelane_b32 v255, s4, 30
	s_lshl_b64 s[14:15], s[6:7], 14
	s_lshl_b32 s4, s95, 6
	s_mov_b64 s[12:13], s[68:69]
	s_or_b32 s14, s14, s4
	s_add_u32 s16, s12, 0xe300000
	s_mul_i32 s4, s15, 0x2a00
	s_mul_hi_u32 s7, s14, 0x2a00
	s_addc_u32 s17, s13, 0
	s_add_i32 s7, s7, s4
	s_mul_i32 s4, s14, 0x2a00
	s_add_u32 s9, s16, s4
	s_addc_u32 s7, s17, s7
	s_lshl_b32 s18, s8, 7
	s_lshl_b32 s4, s8, 8
	v_mov_b32_e32 v53, v195
	s_add_u32 s10, s9, s4
	s_addc_u32 s11, s7, 0
	v_lshlrev_b32_e32 v41, 3, v53
	v_ashrrev_i32_e32 v40, 4, v53
	v_mov_b64_e32 v[0:1], s[10:11]
	v_and_b32_e32 v42, 0x78, v41
	v_mad_i64_i32 v[2:3], s[10:11], v40, s2, v[0:1]
	v_lshlrev_b32_e32 v112, 1, v42
	v_lshl_add_u64 v[10:11], v[2:3], 0, v[112:113]
	v_add_u32_e32 v2, 32, v40
	v_mad_i64_i32 v[0:1], s[10:11], v2, s2, v[0:1]
	v_ashrrev_i32_e32 v43, 31, v53
	v_lshl_add_u64 v[36:37], v[0:1], 0, v[112:113]
	v_lshrrev_b32_e32 v0, 29, v43
	v_add_u32_e32 v0, v53, v0
	v_ashrrev_i32_e32 v4, 3, v0
	v_and_b32_e32 v0, -8, v0
	v_ashrrev_i32_e32 v5, 31, v4
	v_sub_u32_e32 v9, v53, v0
	v_lshl_add_u64 v[0:1], s[14:15], 0, v[4:5]
	v_writelane_b32 v255, s16, 31
	v_ashrrev_i32_e32 v6, 3, v53
	v_ashrrev_i32_e32 v7, 31, v6
	v_mov_b64_e32 v[12:13], s[16:17]
	v_writelane_b32 v255, s17, 32
	v_mad_u64_u32 v[2:3], s[10:11], v0, s2, v[12:13]
	s_mov_b32 s19, s73
	v_mad_i32_i24 v3, v1, s2, v3
	v_writelane_b32 v255, s14, 33
	v_lshl_add_u64 v[0:1], v[2:3], 0, s[18:19]
	v_lshlrev_b32_e32 v2, 3, v9
	v_lshl_add_u64 v[14:15], s[14:15], 0, v[6:7]
	v_mad_u64_u32 v[28:29], s[10:11], v14, s2, v[12:13]
	v_ashrrev_i32_e32 v3, 31, v2
	v_mad_i32_i24 v29, v15, s2, v29
	v_and_b32_e32 v5, 56, v41
	v_lshl_add_u64 v[0:1], v[2:3], 1, v[0:1]
	v_lshl_add_u64 v[20:21], v[28:29], 0, s[18:19]
	v_lshlrev_b32_e32 v112, 1, v5
	global_load_dwordx4 v[0:3], v[0:1], off
	v_lshl_add_u64 v[20:21], v[20:21], 0, v[112:113]
	global_load_dwordx4 v[12:15], v[28:29], off offset:2048
	global_load_dwordx4 v[16:19], v[28:29], off offset:2064
	s_nop 0
	global_load_dwordx4 v[20:23], v[20:21], off offset:512
	s_nop 0
	global_load_dwordx4 v[24:27], v[28:29], off offset:2080
	s_nop 0
	global_load_dwordx4 v[28:31], v[28:29], off offset:2096
	s_nop 0
	global_load_dwordx4 v[32:35], v[10:11], off offset:1024
	s_nop 0
	global_load_dwordx4 v[36:39], v[36:37], off offset:1024
	v_lshlrev_b32_e32 v7, 1, v40
	v_and_b32_e32 v10, -8, v40
	v_and_b32_e32 v7, 14, v7
	s_mov_b32 s2, s0
	v_bitop3_b32 v11, v40, v5, -8 bitop3:0x6c
	v_add_u32_e32 v10, 32, v10
	v_writelane_b32 v255, s15, 34
	s_mov_b32 s10, s18
	v_add_u32_e32 v7, s2, v7
	v_lshlrev_b32_e32 v11, 1, v11
	v_mul_u32_u24_e32 v40, 0x90, v42
	v_bitop3_b32 v10, v10, v41, 56 bitop3:0x78
	v_writelane_b32 v255, s10, 35
	v_add3_u32 v11, v7, v11, v40
	v_lshlrev_b32_e32 v10, 1, v10
	v_ashrrev_i32_e32 v8, 6, v53
	v_writelane_b32 v255, s11, 36
	s_waitcnt lgkmcnt(0)
	s_barrier
; template <int TYPE>
; __device__ __forceinline__ void pass3_item(const KArgs& a, int l, int item, LAS unsigned char* lds) {
;     ...
;     __syncthreads();
;     vT_write(vr, lds, tid);
;     float qf[DK / 64][8];
; #pragma unroll
;     for (int e2 = 0; e2 < DK / 64; ++e2) { unpack8(qraw[e2], qf[e2]);
; #pragma unroll
;         for (int e = 0; e < 8; ++e) qf[e2][e] = TYPE ? silu_(qf[e2][e]) : qf[e2][e] * 0.125f; }
;     f32x4 o[4];
; #pragma unroll
;     for (int it = 0; it < 4; ++it) o[it] = (f32x4){0.f, 0.f, 0.f, 0.f};
; #pragma unroll 1
;     for (int dir = 0; dir < 2; ++dir) {
;         const int sitem = ((b * 4 + h) * 2 + dir) * NCH + c;
;         const bf16_t* ST = (const bf16_t*)(wsb + (TYPE ? WS_SH : WS_SG)) + (size_t)sitem * 128 * DK + (size_t)(wid * 16 + fr) * DK + fq * 8;
;         bf16x8 sf[DK / 32];
; #pragma unroll
;         for (int ks = 0; ks < DK / 32; ++ks) sf[ks] = *(const bf16x8*)(ST + ks * 32);
;         if (dir) __syncthreads();
;         { LgRaw rw; rw.a0 = dir ? raw1.a0 : raw0.a0; rw.a1 = dir ? raw1.a1 : raw0.a1; rw.k = dir ? raw1.k : raw0.k; lg_compute<TYPE>(a, wsb, l, h, dir, rw, lds, tid); }
;         cumsum_g<TYPE>(dir, lds, tid);
; #pragma unroll
;         for (int e2 = 0; e2 < DK / 64; ++e2) { const int task = tid + 512 * e2, i = task / C::ND8, d8 = task % C::ND8;
;             const f32x4 g0 = *(LAS f32x4*)(G + i * C::LDG + d8 * 8), g1 = *(LAS f32x4*)(G + i * C::LDG + d8 * 8 + 4);
;             const f32x4 m0 = *(LAS f32x4*)(G + 32 * C::LDG + d8 * 8), m1 = *(LAS f32x4*)(G + 32 * C::LDG + d8 * 8 + 4);
;             float kk[8], qq[8], qt[8], qg[8]; unpack8(*(LAS bf16x8*)(Kb + i * C::LDK_ + d8 * 8), kk);
; #pragma unroll
;             for (int e = 0; e < 8; ++e) qq[e] = qf[e2][e];
; #pragma unroll
;             for (int e = 0; e < 8; ++e) { const float gg = e < 4 ? g0[e] : g1[e - 4], gm = e < 4 ? m0[e] : m1[e - 4];
;                 const float q = qq[e];
;                 qt[e] = q * __expf(gg - gm); qg[e] = q * __expf(gg); kk[e] = kk[e] * __expf(gm - gg); }
;             *(LAS bf16x8*)(QT + i * C::LDK_ + d8 * 8) = pack8(qt); *(LAS bf16x8*)(QG + i * C::LDK_ + d8 * 8) = pack8(qg); *(LAS bf16x8*)(Kb + i * C::LDK_ + d8 * 8) = pack8(kk); }
;         __syncthreads();
;         { const int it = wid >> 1;
; #pragma unroll
;           for (int jj = 0; jj < 2; ++jj) { const int jt = 2 * (wid & 1) + jj;
	v_add3_u32 v7, v7, v10, v40
	s_mov_b32 s10, 0x3e000000
	v_and_b32_e32 v67, 15, v53
	v_lshlrev_b32_e32 v52, 4, v8
	s_lshl_b32 s6, s6, 3
	s_lshl_b32 s7, s8, 1
	v_writelane_b32 v255, s12, 37
	v_mov_b32_e32 v63, v113
	s_or_b32 s81, s7, s6
	s_mov_b64 s[6:7], 0x31700000
	s_movk_i32 s38, 0x110
	v_writelane_b32 v255, s13, 38
	s_movk_i32 s39, 0x880
	v_cmp_gt_i32_e64 s[20:21], s67, v53
	s_waitcnt vmcnt(0)
	ds_write_b16 v11, v32
	ds_write_b16_d16_hi v11, v32 offset:144
	ds_write_b16 v11, v33 offset:288
	ds_write_b16_d16_hi v11, v33 offset:432
	ds_write_b16 v11, v34 offset:576
	ds_write_b16_d16_hi v11, v34 offset:720
	ds_write_b16 v11, v35 offset:864
	ds_write_b16_d16_hi v11, v35 offset:1008
	v_and_b32_e32 v11, 0xffff0000, v0
	v_lshlrev_b32_e32 v10, 16, v0
	v_pk_mul_f32 v[54:55], v[10:11], s[10:11] op_sel_hi:[1,0]
	v_and_b32_e32 v11, 0xffff0000, v1
	v_lshlrev_b32_e32 v10, 16, v1
	v_pk_mul_f32 v[56:57], v[10:11], s[10:11] op_sel_hi:[1,0]
	v_and_b32_e32 v1, 0xffff0000, v2
	v_lshlrev_b32_e32 v0, 16, v2
	v_or_b32_e32 v10, v52, v67
	v_pk_mul_f32 v[58:59], v[0:1], s[10:11] op_sel_hi:[1,0]
	v_and_b32_e32 v1, 0xffff0000, v3
	v_lshlrev_b32_e32 v0, 16, v3
	v_ashrrev_i32_e32 v11, 31, v10
	v_pk_mul_f32 v[60:61], v[0:1], s[10:11] op_sel_hi:[1,0]
	v_bfe_u32 v3, v53, 4, 2
	v_lshlrev_b64 v[0:1], 7, v[10:11]
	v_lshl_add_u64 v[0:1], s[12:13], 0, v[0:1]
	v_lshlrev_b32_e32 v62, 4, v3
	v_lshl_add_u64 v[0:1], v[0:1], 0, v[62:63]
	v_lshl_add_u64 v[64:65], v[0:1], 0, s[6:7]
	v_mul_lo_u32 v0, v6, s38
	v_add_u32_e32 v0, 0, v0
	v_lshlrev_b32_e32 v2, 2, v5
	v_lshlrev_b32_e32 v1, 7, v6
	v_add_u32_e32 v83, v0, v2
	v_sub_u32_e32 v0, v0, v1
	v_add_u32_e32 v85, v0, v112
	v_lshrrev_b32_e32 v0, 26, v43
	v_add_u32_e32 v0, v53, v0
	v_ashrrev_i32_e32 v1, 6, v0
	v_and_b32_e32 v0, 0x3fffffc0, v0
	v_sub_u32_e32 v0, v53, v0
	v_lshlrev_b32_e32 v0, 2, v0
	v_add_u32_e32 v66, 0, v0
	v_add_u32_e32 v89, s74, v0
	s_movk_i32 s6, 0xffc1
	v_mul_lo_u32 v0, v4, s38
	v_cmp_gt_i32_e64 s[6:7], s6, v53
	v_add_u32_e32 v0, 0, v0
	v_lshlrev_b32_e32 v5, 5, v9
	v_writelane_b32 v255, s6, 39
	v_add_u32_e32 v94, v0, v5
	v_add_u32_e32 v95, 0, v5
	v_lshlrev_b32_e32 v5, 7, v4
	v_writelane_b32 v255, s7, 40
	v_sub_u32_e32 v0, v0, v5
	v_lshlrev_b32_e32 v5, 4, v9
	v_add_u32_e32 v96, v0, v5
	v_mul_lo_u32 v0, v4, s3
	v_readlane_b32 s70, v255, 8
	v_lshlrev_b32_e32 v63, 2, v3
	ds_write_b16 v7, v36
	ds_write_b16_d16_hi v7, v36 offset:144
	ds_write_b16 v7, v37 offset:288
	ds_write_b16_d16_hi v7, v37 offset:432
	ds_write_b16 v7, v38 offset:576
	ds_write_b16_d16_hi v7, v38 offset:720
	ds_write_b16 v7, v39 offset:864
	ds_write_b16_d16_hi v7, v39 offset:1008
	v_add3_u32 v97, s70, v0, v5
	v_and_b32_e32 v5, -16, v6
	v_lshlrev_b32_e32 v7, 3, v3
	v_lshlrev_b32_e32 v87, 3, v1
	v_lshl_add_u32 v93, v1, 9, v89
	v_mul_lo_u32 v1, v1, s39
	v_bfi_b32 v6, -16, v6, v53
	v_add_u32_e32 v0, 0, v62
	v_or_b32_e32 v3, v63, v5
	v_mul_lo_u32 v5, v10, s3
	v_lshlrev_b32_e32 v4, 5, v8
	v_mad_u64_u32 v[68:69], s[38:39], v6, s3, v[0:1]
	v_add_u32_e32 v5, s2, v5
	v_bitop3_b32 v6, v52, 56, v67 bitop3:0xc8
	v_bitop3_b32 v8, v10, v7, 56 bitop3:0x6c
	v_lshl_add_u32 v69, v8, 1, v5
	v_bitop3_b32 v6, v7, v6, 32 bitop3:0x36
	v_and_or_b32 v7, v4, 32, v67
	v_readlane_b32 s71, v255, 9
	v_or_b32_e32 v8, 1, v3
	v_or_b32_e32 v9, 2, v3
	v_or_b32_e32 v10, 3, v3
	v_lshl_add_u32 v98, v6, 1, v5
	v_mul_u32_u24_e32 v4, 0x90, v7
	v_lshl_add_u32 v5, v7, 1, s71
	v_cmp_ge_i32_e64 s[38:39], v7, v3
	v_cmp_le_i32_e64 s[40:41], v7, v3
	v_cmp_gt_i32_e64 s[42:43], v7, v3
	v_cmp_le_i32_e64 s[44:45], v7, v8
	v_cmp_ge_i32_e64 s[50:51], v7, v9
	v_cmp_le_i32_e64 s[52:53], v7, v9
	v_cmp_ge_i32_e64 s[54:55], v7, v10
	v_cmp_le_i32_e64 s[90:91], v7, v10
	v_or_b32_e32 v7, 16, v7
	v_mul_lo_u32 v6, v3, s3
	v_cmp_ge_i32_e64 s[2:3], v7, v3
	v_cmp_le_i32_e64 s[56:57], v7, v3
	v_cmp_gt_i32_e64 s[58:59], v7, v3
	v_mul_u32_u24_e32 v3, 0x48, v67
	v_lshlrev_b32_e32 v3, 1, v3
	v_cmp_gt_i32_e64 s[12:13], s66, v53
	v_lshlrev_b32_e32 v11, 1, v7
	v_cmp_le_i32_e64 s[60:61], v7, v8
	v_cmp_ge_i32_e64 s[62:63], v7, v9
	v_cmp_le_i32_e64 s[64:65], v7, v9
	v_cmp_ge_i32_e64 s[66:67], v7, v10
	v_cmp_le_i32_e64 s[68:69], v7, v10
	v_add_u32_e32 v7, s71, v62
	v_add_u32_e32 v8, 0x900, v3
	v_add_u32_e32 v103, v7, v3
	v_add3_u32 v104, s70, v62, v3
	v_add_u32_e32 v105, v7, v8
	v_add3_u32 v106, s71, v8, v62
	v_add_u32_e32 v8, 0x1200, v3
	v_add_u32_e32 v3, 0x1b00, v3
	s_add_u32 s70, s46, s4
	v_add3_u32 v99, s71, v6, v11
	v_add3_u32 v108, s71, v8, v62
	v_add_u32_e32 v109, v7, v3
	v_add3_u32 v110, s71, v3, v62
	s_addc_u32 s71, s47, 0
	v_mov_b32_e32 v3, v113
	v_lshl_add_u64 v[70:71], s[70:71], 0, v[2:3]
	s_add_u32 s70, s48, s4
	s_movk_i32 s10, 0x7f
	s_movk_i32 s14, 0xbf
	s_movk_i32 s16, 0xc0
	s_movk_i32 s18, 0xff
	s_movk_i32 s22, 0x13f
	s_movk_i32 s24, 0x140
	s_movk_i32 s26, 0x17f
	s_movk_i32 s28, 0x180
	s_movk_i32 s30, 0x1bf
	s_movk_i32 s34, 0x1c0
	s_movk_i32 s36, 0x1ff
	s_addc_u32 s71, s49, 0
	v_mov_b32_e32 v32, 0
	v_cmp_lt_i32_e64 s[82:83], 63, v53
	v_cmp_gt_i32_e64 s[6:7], 64, v53
	v_cmp_lt_i32_e64 s[10:11], s10, v53
	v_cmp_lt_i32_e64 s[14:15], s14, v53
	v_cmp_gt_i32_e64 s[16:17], s16, v53
	v_cmp_lt_i32_e64 s[18:19], s18, v53
	v_cmp_lt_i32_e64 s[22:23], s22, v53
	v_cmp_gt_i32_e64 s[24:25], s24, v53
	v_cmp_lt_i32_e64 s[26:27], s26, v53
	v_cmp_gt_i32_e64 s[28:29], s28, v53
	v_cmp_lt_i32_e64 s[30:31], s30, v53
	v_cmp_gt_i32_e64 s[34:35], s34, v53
	v_cmp_lt_i32_e64 s[36:37], s36, v53
	v_add_u32_e32 v100, 0x90, v99
	v_add_u32_e32 v101, 0x120, v99
	v_add_u32_e32 v102, 0x1b0, v99
	v_add_u32_e32 v107, v7, v8
	v_lshl_add_u64 v[72:73], s[70:71], 0, v[2:3]
	s_mov_b32 s70, 0
	s_mov_b64 s[84:85], -1
	v_add_u32_e32 v111, v66, v1
	v_add_u32_e32 v112, v0, v4
	v_add_u32_e32 v114, v5, v6
	v_mov_b32_e32 v33, v32
	v_mov_b32_e32 v34, v32
	v_mov_b32_e32 v35, v32
	v_mov_b32_e32 v8, v32
	v_mov_b32_e32 v9, v32
	v_mov_b32_e32 v10, v32
	v_mov_b32_e32 v11, v32
	v_mov_b32_e32 v4, v32
	v_mov_b32_e32 v5, v32
	v_mov_b32_e32 v6, v32
	v_mov_b32_e32 v7, v32
	v_mov_b32_e32 v0, v32
	v_mov_b32_e32 v1, v32
	v_mov_b32_e32 v2, v32
	v_mov_b32_e32 v3, v32
	s_branch .LBB0_512
